# strategy: one static s_setprio 1 for waves 4-7 around the phase 3 / phase 12 K-loops, per-segment priority flips deleted
# speedup vs baseline: 1.0079x; 1.0079x over previous
; #define PG8_STAGE(bufoff, gbase, voff) do { _Pragma("unroll") for (int _i = 0; _i < 2; ++_i) \
;         __builtin_amdgcn_global_load_lds((const unsigned*)((const char*)(gbase) + (voff)[_i]), (LAS unsigned*)(lds + (bufoff) + ldsw + _i * 8192), 16, 0, 0); } while (0)
; #define PG8_LDA(dst, b, h) do { _Pragma("unroll") for (int m = 0; m < 4; ++m) _Pragma("unroll") for (int k = 0; k < 2; ++k) dst[m][k] = *(const LAS bf16x8*)(lds + PG8_SA(b, h) + aoff + m * 2048 + k * 1024); } while (0)
; #define PG8_LDB(dst, b, h) do { _Pragma("unroll") for (int n = 0; n < 2; ++n) _Pragma("unroll") for (int k = 0; k < 2; ++k) dst[n][k] = *(const LAS bf16x8*)(lds + PG8_SB(b, h) + boff + n * 2048 + k * 1024); } while (0)
; #define PG8_MMA(ai, bj, At, Bt) do { __builtin_amdgcn_s_setprio(1); _Pragma("unroll") for (int m = 0; m < 4; ++m) _Pragma("unroll") for (int n = 0; n < 2; ++n) _Pragma("unroll") for (int k = 0; k < 2; ++k) \
;         acc[ai][bj][m][n] = __builtin_amdgcn_mfma_f32_16x16x32_bf16(Bt[n][k], At[m][k], acc[ai][bj][m][n], 0, 0, 0); __builtin_amdgcn_s_setprio(0); } while (0)
; #define PG8_WAIT_L(n) asm volatile("s_waitcnt lgkmcnt(" #n ")" ::: "memory")
; #define PG8_BAR __builtin_amdgcn_s_barrier()
; #define PG8_SCHED __builtin_amdgcn_sched_barrier(0)
; template <class Epi, class Sched>
; __device__ __forceinline__ void gemm_phase(LAS unsigned char* lds, const Gemm g, const Sched& S, const Epi& E) {
;     ...
;         for (int t = 0; t < nt; t += 2) {
;             const bool last = (t == nt - 2);
;             const char* a1 = cA + (size_t)(t + 1) * kstep;
;             const char* a2 = last ? nA : cA + (size_t)(t + 2) * kstep; const char* b2 = last ? nB : cB + (size_t)(t + 2) * kstep;
;             const char* a3 = a2 + kstep; const char* b3 = b2 + kstep;
;             PG8_LDB(B0, 0, 0); PG8_SCHED; PG8_LDA(At, 0, 0); PG8_STAGE(PG8_SA(1, 1), a1 + hstepA, voffA);
;             PG8_WAIT_L(8); PG8_BAR; PG8_WAIT_L(0); PG8_MMA(0, 0, At, B0); PG8_BAR; PG8_SCHED;
;     ...
;         for (int a = 0; a < 2; ++a)
; #pragma unroll
;             for (int b = 0; b < 2; ++b)
; #pragma unroll
;                 for (int m = 0; m < 4; ++m)
; #pragma unroll
;                     for (int n = 0; n < 2; ++n) acc[a][b][m][n] = (f32x4){0.f, 0.f, 0.f, 0.f};
;         cur = nxt; cA = nA; cB = nB; ++ui;
.LBB0_474:
	s_ashr_i32 s17, s16, 31
	v_cmp_lt_i64_e32 vcc, s[18:19], v[140:141]
	s_lshl_b64 s[18:19], s[16:17], 20
	s_add_u32 s18, s28, s18
	s_addc_u32 s19, s29, s19
	s_and_b64 s[20:21], vcc, exec
	s_cselect_b32 s17, s19, s23
	s_cselect_b32 s45, s18, s22
	s_ashr_i32 s15, s14, 31
	s_lshl_b64 s[20:21], s[14:15], 20
	s_add_u32 s20, s84, s20
	s_addc_u32 s21, s85, s21
	s_and_b64 s[26:27], vcc, exec
	s_cselect_b32 s15, s21, s25
	s_cselect_b32 s46, s20, s24
	s_add_u32 s22, s22, 0x80080
	s_addc_u32 s23, s23, 0
	s_add_u32 s47, s24, 0x100
	v_mov_b32_e32 v0, 0
	s_addc_u32 s48, s25, 0
	s_mov_b32 s49, -2
	v_mov_b32_e32 v1, v0
	v_mov_b32_e32 v2, v0
	v_mov_b32_e32 v3, v0
	v_mov_b32_e32 v4, v0
	v_mov_b32_e32 v5, v0
	v_mov_b32_e32 v6, v0
	v_mov_b32_e32 v7, v0
	v_mov_b32_e32 v8, v0
	v_mov_b32_e32 v9, v0
	v_mov_b32_e32 v10, v0
	v_mov_b32_e32 v11, v0
	v_mov_b32_e32 v12, v0
	v_mov_b32_e32 v13, v0
	v_mov_b32_e32 v14, v0
	v_mov_b32_e32 v15, v0
	v_mov_b32_e32 v24, v0
	v_mov_b32_e32 v25, v0
	v_mov_b32_e32 v26, v0
	v_mov_b32_e32 v27, v0
	v_mov_b32_e32 v28, v0
	v_mov_b32_e32 v29, v0
	v_mov_b32_e32 v30, v0
	v_mov_b32_e32 v31, v0
	v_mov_b32_e32 v40, v0
	v_mov_b32_e32 v41, v0
	v_mov_b32_e32 v42, v0
	v_mov_b32_e32 v43, v0
	v_mov_b32_e32 v44, v0
	v_mov_b32_e32 v45, v0
	v_mov_b32_e32 v46, v0
	v_mov_b32_e32 v47, v0
	v_mov_b32_e32 v16, v0
	v_mov_b32_e32 v17, v0
	v_mov_b32_e32 v18, v0
	v_mov_b32_e32 v19, v0
	v_mov_b32_e32 v20, v0
	v_mov_b32_e32 v21, v0
	v_mov_b32_e32 v22, v0
	v_mov_b32_e32 v23, v0
	v_mov_b32_e32 v32, v0
	v_mov_b32_e32 v33, v0
	v_mov_b32_e32 v34, v0
	v_mov_b32_e32 v35, v0
	v_mov_b32_e32 v36, v0
	v_mov_b32_e32 v37, v0
	v_mov_b32_e32 v38, v0
	v_mov_b32_e32 v39, v0
	v_mov_b32_e32 v48, v0
	v_mov_b32_e32 v49, v0
	v_mov_b32_e32 v50, v0
	v_mov_b32_e32 v51, v0
	v_mov_b32_e32 v52, v0
	v_mov_b32_e32 v53, v0
	v_mov_b32_e32 v54, v0
	v_mov_b32_e32 v55, v0
	v_mov_b32_e32 v56, v0
	v_mov_b32_e32 v57, v0
	v_mov_b32_e32 v58, v0
	v_mov_b32_e32 v59, v0
	v_mov_b32_e32 v60, v0
	v_mov_b32_e32 v61, v0
	v_mov_b32_e32 v62, v0
	v_mov_b32_e32 v63, v0
	v_mov_b32_e32 v64, v0
	v_mov_b32_e32 v65, v0
	v_mov_b32_e32 v66, v0
	v_mov_b32_e32 v67, v0
	v_mov_b32_e32 v68, v0
	v_mov_b32_e32 v69, v0
	v_mov_b32_e32 v70, v0
	v_mov_b32_e32 v71, v0
	v_mov_b32_e32 v72, v0
	v_mov_b32_e32 v73, v0
	v_mov_b32_e32 v74, v0
	v_mov_b32_e32 v75, v0
	v_mov_b32_e32 v76, v0
	v_mov_b32_e32 v77, v0
	v_mov_b32_e32 v78, v0
	v_mov_b32_e32 v79, v0
	v_mov_b32_e32 v88, v0
	v_mov_b32_e32 v89, v0
	v_mov_b32_e32 v90, v0
	v_mov_b32_e32 v91, v0
	v_mov_b32_e32 v92, v0
	v_mov_b32_e32 v93, v0
	v_mov_b32_e32 v94, v0
	v_mov_b32_e32 v95, v0
	v_mov_b32_e32 v104, v0
	v_mov_b32_e32 v105, v0
	v_mov_b32_e32 v106, v0
	v_mov_b32_e32 v107, v0
	v_mov_b32_e32 v108, v0
	v_mov_b32_e32 v109, v0
	v_mov_b32_e32 v110, v0
	v_mov_b32_e32 v111, v0
	v_mov_b32_e32 v80, v0
	v_mov_b32_e32 v81, v0
	v_mov_b32_e32 v82, v0
	v_mov_b32_e32 v83, v0
	v_mov_b32_e32 v84, v0
	v_mov_b32_e32 v85, v0
	v_mov_b32_e32 v86, v0
	v_mov_b32_e32 v87, v0
	v_mov_b32_e32 v96, v0
	v_mov_b32_e32 v97, v0
	v_mov_b32_e32 v98, v0
	v_mov_b32_e32 v99, v0
	v_mov_b32_e32 v100, v0
	v_mov_b32_e32 v101, v0
	v_mov_b32_e32 v102, v0
	v_mov_b32_e32 v103, v0
	v_mov_b32_e32 v112, v0
	v_mov_b32_e32 v113, v0
	v_mov_b32_e32 v114, v0
	v_mov_b32_e32 v115, v0
	v_mov_b32_e32 v116, v0
	v_mov_b32_e32 v117, v0
	v_mov_b32_e32 v118, v0
	v_mov_b32_e32 v119, v0
	v_mov_b32_e32 v120, v0
	v_mov_b32_e32 v121, v0
	v_mov_b32_e32 v122, v0
	v_mov_b32_e32 v123, v0
	v_mov_b32_e32 v124, v0
	v_mov_b32_e32 v125, v0
	v_mov_b32_e32 v126, v0
	v_mov_b32_e32 v127, v0
	s_lshr_b32 s57, s3, 8
	s_cmp_lg_u32 s57, 0
	s_cbranch_scc0 .Lprio_475
	s_setprio 1
.Lprio_475:
.LBB0_475:
	ds_read_b128 v[150:153], v147
	ds_read_b128 v[154:157], v147 offset:1024
	ds_read_b128 v[162:165], v147 offset:2048
	ds_read_b128 v[168:171], v147 offset:3072
	s_add_u32 s24, s22, 0xfff80080
	s_addc_u32 s25, s23, -1
	s_cmp_eq_u32 s49, 28
	s_cselect_b32 s27, s17, s25
	s_cselect_b32 s26, s45, s24
	s_cselect_b32 s25, s15, s48
	s_cselect_b32 s24, s46, s47
	v_lshl_add_u64 v[158:159], s[22:23], 0, v[136:137]
	s_add_i32 m0, s13, 0xc000
	ds_read_b128 v[172:175], v148
	ds_read_b128 v[176:179], v148 offset:1024
	ds_read_b128 v[180:183], v148 offset:2048
	ds_read_b128 v[186:189], v148 offset:3072
	ds_read_b128 v[190:193], v148 offset:4096
	ds_read_b128 v[194:197], v148 offset:5120
	ds_read_b128 v[198:201], v148 offset:6144
	ds_read_b128 v[202:205], v148 offset:7168
	global_load_lds_dwordx4 v[158:159], off
	v_lshl_add_u64 v[158:159], s[22:23], 0, v[138:139]
	s_add_i32 m0, s13, 0xe000
	s_nop 0
	global_load_lds_dwordx4 v[158:159], off
	s_waitcnt lgkmcnt(8)
	s_barrier
	s_waitcnt lgkmcnt(0)
	s_waitcnt lgkmcnt(0)
	v_mfma_f32_16x16x32_bf16 v[124:127], v[150:153], v[172:175], v[124:127]
	v_mfma_f32_16x16x32_bf16 v[120:123], v[162:165], v[172:175], v[120:123]
	v_mfma_f32_16x16x32_bf16 v[116:119], v[150:153], v[180:183], v[116:119]
	v_mfma_f32_16x16x32_bf16 v[112:115], v[162:165], v[180:183], v[112:115]
	v_mfma_f32_16x16x32_bf16 v[100:103], v[150:153], v[190:193], v[100:103]
	v_mfma_f32_16x16x32_bf16 v[96:99], v[162:165], v[190:193], v[96:99]
	v_mfma_f32_16x16x32_bf16 v[84:87], v[150:153], v[198:201], v[84:87]
	v_mfma_f32_16x16x32_bf16 v[80:83], v[162:165], v[198:201], v[80:83]
	v_mfma_f32_16x16x32_bf16 v[124:127], v[154:157], v[176:179], v[124:127]
	v_mfma_f32_16x16x32_bf16 v[120:123], v[168:171], v[176:179], v[120:123]
	v_mfma_f32_16x16x32_bf16 v[116:119], v[154:157], v[186:189], v[116:119]
	v_mfma_f32_16x16x32_bf16 v[112:115], v[168:171], v[186:189], v[112:115]
	v_mfma_f32_16x16x32_bf16 v[100:103], v[154:157], v[194:197], v[100:103]
	v_mfma_f32_16x16x32_bf16 v[96:99], v[168:171], v[194:197], v[96:99]
	v_mfma_f32_16x16x32_bf16 v[84:87], v[154:157], v[202:205], v[84:87]
	v_mfma_f32_16x16x32_bf16 v[80:83], v[168:171], v[202:205], v[80:83]
	s_barrier
; #define PG8_STAGE(bufoff, gbase, voff) do { _Pragma("unroll") for (int _i = 0; _i < 2; ++_i) \
;         __builtin_amdgcn_global_load_lds((const unsigned*)((const char*)(gbase) + (voff)[_i]), (LAS unsigned*)(lds + (bufoff) + ldsw + _i * 8192), 16, 0, 0); } while (0)
; #define PG8_LDA(dst, b, h) do { _Pragma("unroll") for (int m = 0; m < 4; ++m) _Pragma("unroll") for (int k = 0; k < 2; ++k) dst[m][k] = *(const LAS bf16x8*)(lds + PG8_SA(b, h) + aoff + m * 2048 + k * 1024); } while (0)
; #define PG8_LDB(dst, b, h) do { _Pragma("unroll") for (int n = 0; n < 2; ++n) _Pragma("unroll") for (int k = 0; k < 2; ++k) dst[n][k] = *(const LAS bf16x8*)(lds + PG8_SB(b, h) + boff + n * 2048 + k * 1024); } while (0)
; #define PG8_MMA(ai, bj, At, Bt) do { __builtin_amdgcn_s_setprio(1); _Pragma("unroll") for (int m = 0; m < 4; ++m) _Pragma("unroll") for (int n = 0; n < 2; ++n) _Pragma("unroll") for (int k = 0; k < 2; ++k) \
;         acc[ai][bj][m][n] = __builtin_amdgcn_mfma_f32_16x16x32_bf16(Bt[n][k], At[m][k], acc[ai][bj][m][n], 0, 0, 0); __builtin_amdgcn_s_setprio(0); } while (0)
; #define PG8_WAIT_V(n) asm volatile("s_waitcnt vmcnt(" #n ")" ::: "memory")
; #define PG8_WAIT_L(n) asm volatile("s_waitcnt lgkmcnt(" #n ")" ::: "memory")
; #define PG8_BAR __builtin_amdgcn_s_barrier()
; #define PG8_SCHED __builtin_amdgcn_sched_barrier(0)
; template <class Epi, class Sched>
; __device__ __forceinline__ void gemm_phase(LAS unsigned char* lds, const Gemm g, const Sched& S, const Epi& E) {
;     ...
;             PG8_LDB(B1, 0, 1); PG8_STAGE(PG8_SB(0, 0), b2, voffB);
;             PG8_BAR; PG8_WAIT_L(0); if constexpr (!Epi::DIAG) PG8_MMA(0, 1, At, B1); PG8_BAR;
;             PG8_LDA(At, 0, 1); PG8_STAGE(PG8_SA(0, 0), a2, voffA);
;             PG8_BAR; PG8_WAIT_L(0); if constexpr (!Epi::DIAG) PG8_MMA(1, 0, At, B0); PG8_BAR; PG8_SCHED;
;             PG8_STAGE(PG8_SB(0, 1), b2 + hstepB, voffB);
;             PG8_WAIT_V(6); PG8_BAR; PG8_MMA(1, 1, At, B1); PG8_BAR;
;             PG8_LDB(B0, 1, 0); PG8_SCHED; PG8_LDA(At, 1, 0); PG8_STAGE(PG8_SA(0, 1), a2 + hstepA, voffA);
;             PG8_WAIT_L(8); PG8_BAR; PG8_WAIT_L(0); PG8_MMA(0, 0, At, B0); PG8_BAR; PG8_SCHED;
	s_add_i32 s50, s41, s30
	v_lshl_add_u64 v[158:159], s[24:25], 0, v[130:131]
	s_mov_b32 m0, s50
	ds_read_b128 v[206:209], v149
	ds_read_b128 v[210:213], v149 offset:1024
	ds_read_b128 v[214:217], v149 offset:2048
	ds_read_b128 v[218:221], v149 offset:3072
	global_load_lds_dwordx4 v[158:159], off
	v_lshl_add_u64 v[222:223], s[24:25], 0, v[134:135]
	s_add_i32 m0, s50, 0x2000
	s_nop 0
	global_load_lds_dwordx4 v[222:223], off
	s_barrier
	s_waitcnt lgkmcnt(0)
	s_waitcnt lgkmcnt(0)
	v_mfma_f32_16x16x32_bf16 v[108:111], v[206:209], v[172:175], v[108:111]
	v_mfma_f32_16x16x32_bf16 v[104:107], v[214:217], v[172:175], v[104:107]
	v_mfma_f32_16x16x32_bf16 v[92:95], v[206:209], v[180:183], v[92:95]
	v_mfma_f32_16x16x32_bf16 v[88:91], v[214:217], v[180:183], v[88:91]
	v_mfma_f32_16x16x32_bf16 v[76:79], v[206:209], v[190:193], v[76:79]
	v_mfma_f32_16x16x32_bf16 v[72:75], v[214:217], v[190:193], v[72:75]
	v_mfma_f32_16x16x32_bf16 v[68:71], v[206:209], v[198:201], v[68:71]
	v_mfma_f32_16x16x32_bf16 v[64:67], v[214:217], v[198:201], v[64:67]
	v_mfma_f32_16x16x32_bf16 v[108:111], v[210:213], v[176:179], v[108:111]
	v_mfma_f32_16x16x32_bf16 v[104:107], v[218:221], v[176:179], v[104:107]
	v_mfma_f32_16x16x32_bf16 v[92:95], v[210:213], v[186:189], v[92:95]
	v_mfma_f32_16x16x32_bf16 v[88:91], v[218:221], v[186:189], v[88:91]
	v_mfma_f32_16x16x32_bf16 v[76:79], v[210:213], v[194:197], v[76:79]
	v_mfma_f32_16x16x32_bf16 v[72:75], v[218:221], v[194:197], v[72:75]
	v_mfma_f32_16x16x32_bf16 v[68:71], v[210:213], v[202:205], v[68:71]
	v_mfma_f32_16x16x32_bf16 v[64:67], v[218:221], v[202:205], v[64:67]
	s_mov_b32 m0, s13
	v_lshl_add_u64 v[224:225], s[26:27], 0, v[128:129]
	s_barrier
	ds_read_b128 v[172:175], v148 offset:16384
	ds_read_b128 v[176:179], v148 offset:17408
	ds_read_b128 v[180:183], v148 offset:18432
	ds_read_b128 v[186:189], v148 offset:19456
	ds_read_b128 v[190:193], v148 offset:20480
	ds_read_b128 v[194:197], v148 offset:21504
	ds_read_b128 v[198:201], v148 offset:22528
	ds_read_b128 v[202:205], v148 offset:23552
	global_load_lds_dwordx4 v[224:225], off
	v_lshl_add_u64 v[226:227], s[26:27], 0, v[132:133]
	s_mov_b32 m0, s34
	s_nop 0
	global_load_lds_dwordx4 v[226:227], off
	s_barrier
	s_waitcnt lgkmcnt(0)
	s_waitcnt lgkmcnt(0)
	v_mfma_f32_16x16x32_bf16 v[60:63], v[150:153], v[172:175], v[60:63]
	v_mfma_f32_16x16x32_bf16 v[56:59], v[162:165], v[172:175], v[56:59]
	v_mfma_f32_16x16x32_bf16 v[52:55], v[150:153], v[180:183], v[52:55]
	v_mfma_f32_16x16x32_bf16 v[48:51], v[162:165], v[180:183], v[48:51]
	v_mfma_f32_16x16x32_bf16 v[36:39], v[150:153], v[190:193], v[36:39]
	v_mfma_f32_16x16x32_bf16 v[32:35], v[162:165], v[190:193], v[32:35]
	v_mfma_f32_16x16x32_bf16 v[20:23], v[150:153], v[198:201], v[20:23]
	v_mfma_f32_16x16x32_bf16 v[16:19], v[162:165], v[198:201], v[16:19]
	v_mfma_f32_16x16x32_bf16 v[60:63], v[154:157], v[176:179], v[60:63]
	v_mfma_f32_16x16x32_bf16 v[56:59], v[168:171], v[176:179], v[56:59]
	v_mfma_f32_16x16x32_bf16 v[52:55], v[154:157], v[186:189], v[52:55]
	v_mfma_f32_16x16x32_bf16 v[48:51], v[168:171], v[186:189], v[48:51]
	v_mfma_f32_16x16x32_bf16 v[36:39], v[154:157], v[194:197], v[36:39]
	v_mfma_f32_16x16x32_bf16 v[32:35], v[168:171], v[194:197], v[32:35]
	v_mfma_f32_16x16x32_bf16 v[20:23], v[154:157], v[202:205], v[20:23]
	v_mfma_f32_16x16x32_bf16 v[16:19], v[168:171], v[202:205], v[16:19]
	s_barrier
	s_add_u32 s50, s24, 0x80000
	s_addc_u32 s51, s25, 0
	s_add_i32 s52, s42, s30
	v_lshl_add_u64 v[150:151], s[50:51], 0, v[130:131]
	s_mov_b32 m0, s52
	s_nop 0
	global_load_lds_dwordx4 v[150:151], off
	v_lshl_add_u64 v[150:151], s[50:51], 0, v[134:135]
	s_add_i32 m0, s52, 0x2000
	s_nop 0
	global_load_lds_dwordx4 v[150:151], off
	s_waitcnt vmcnt(6)
	s_barrier
	v_mfma_f32_16x16x32_bf16 v[44:47], v[206:209], v[172:175], v[44:47]
	v_mfma_f32_16x16x32_bf16 v[40:43], v[214:217], v[172:175], v[40:43]
	v_mfma_f32_16x16x32_bf16 v[28:31], v[206:209], v[180:183], v[28:31]
	v_mfma_f32_16x16x32_bf16 v[24:27], v[214:217], v[180:183], v[24:27]
	v_mfma_f32_16x16x32_bf16 v[12:15], v[206:209], v[190:193], v[12:15]
	v_mfma_f32_16x16x32_bf16 v[8:11], v[214:217], v[190:193], v[8:11]
	v_mfma_f32_16x16x32_bf16 v[4:7], v[206:209], v[198:201], v[4:7]
	v_mfma_f32_16x16x32_bf16 v[0:3], v[214:217], v[198:201], v[0:3]
	v_mfma_f32_16x16x32_bf16 v[44:47], v[210:213], v[176:179], v[44:47]
	v_mfma_f32_16x16x32_bf16 v[40:43], v[218:221], v[176:179], v[40:43]
	v_mfma_f32_16x16x32_bf16 v[28:31], v[210:213], v[186:189], v[28:31]
	v_mfma_f32_16x16x32_bf16 v[24:27], v[218:221], v[186:189], v[24:27]
	v_mfma_f32_16x16x32_bf16 v[12:15], v[210:213], v[194:197], v[12:15]
	v_mfma_f32_16x16x32_bf16 v[8:11], v[218:221], v[194:197], v[8:11]
	v_mfma_f32_16x16x32_bf16 v[4:7], v[210:213], v[202:205], v[4:7]
	v_mfma_f32_16x16x32_bf16 v[0:3], v[218:221], v[202:205], v[0:3]
	s_add_i32 s50, 0, 0x18000
	v_add_u32_e32 v161, s50, v145
	s_barrier
	ds_read_b128 v[150:153], v161
	ds_read_b128 v[154:157], v161 offset:1024
	ds_read_b128 v[162:165], v161 offset:2048
	ds_read_b128 v[168:171], v161 offset:3072
	s_add_u32 s26, s26, 0x80000
	s_addc_u32 s27, s27, 0
	s_mov_b32 m0, s35
	v_lshl_add_u64 v[206:207], s[26:27], 0, v[128:129]
	ds_read_b128 v[172:175], v148 offset:32768
	ds_read_b128 v[176:179], v148 offset:33792
	ds_read_b128 v[180:183], v148 offset:34816
	ds_read_b128 v[186:189], v148 offset:35840
	ds_read_b128 v[190:193], v148 offset:36864
	ds_read_b128 v[194:197], v148 offset:37888
	ds_read_b128 v[198:201], v148 offset:38912
	ds_read_b128 v[202:205], v148 offset:39936
	global_load_lds_dwordx4 v[206:207], off
	v_lshl_add_u64 v[206:207], s[26:27], 0, v[132:133]
	s_mov_b32 m0, s36
	s_nop 0
	global_load_lds_dwordx4 v[206:207], off
	s_waitcnt lgkmcnt(8)
	s_barrier
; #define PG8_STAGE(bufoff, gbase, voff) do { _Pragma("unroll") for (int _i = 0; _i < 2; ++_i) \
;         __builtin_amdgcn_global_load_lds((const unsigned*)((const char*)(gbase) + (voff)[_i]), (LAS unsigned*)(lds + (bufoff) + ldsw + _i * 8192), 16, 0, 0); } while (0)
; #define PG8_LDA(dst, b, h) do { _Pragma("unroll") for (int m = 0; m < 4; ++m) _Pragma("unroll") for (int k = 0; k < 2; ++k) dst[m][k] = *(const LAS bf16x8*)(lds + PG8_SA(b, h) + aoff + m * 2048 + k * 1024); } while (0)
; #define PG8_LDB(dst, b, h) do { _Pragma("unroll") for (int n = 0; n < 2; ++n) _Pragma("unroll") for (int k = 0; k < 2; ++k) dst[n][k] = *(const LAS bf16x8*)(lds + PG8_SB(b, h) + boff + n * 2048 + k * 1024); } while (0)
; #define PG8_MMA(ai, bj, At, Bt) do { __builtin_amdgcn_s_setprio(1); _Pragma("unroll") for (int m = 0; m < 4; ++m) _Pragma("unroll") for (int n = 0; n < 2; ++n) _Pragma("unroll") for (int k = 0; k < 2; ++k) \
;         acc[ai][bj][m][n] = __builtin_amdgcn_mfma_f32_16x16x32_bf16(Bt[n][k], At[m][k], acc[ai][bj][m][n], 0, 0, 0); __builtin_amdgcn_s_setprio(0); } while (0)
; #define PG8_WAIT_V(n) asm volatile("s_waitcnt vmcnt(" #n ")" ::: "memory")
; #define PG8_WAIT_L(n) asm volatile("s_waitcnt lgkmcnt(" #n ")" ::: "memory")
; #define PG8_BAR __builtin_amdgcn_s_barrier()
; #define PG8_SCHED __builtin_amdgcn_sched_barrier(0)
; template <class Epi, class Sched>
; __device__ __forceinline__ void gemm_phase(LAS unsigned char* lds, const Gemm g, const Sched& S, const Epi& E) {
;     ...
;             PG8_WAIT_L(8); PG8_BAR; PG8_WAIT_L(0); PG8_MMA(0, 0, At, B0); PG8_BAR; PG8_SCHED;
;             PG8_LDB(B1, 1, 1); PG8_STAGE(PG8_SB(1, 0), b3, voffB);
;             PG8_BAR; PG8_WAIT_L(0); if constexpr (!Epi::DIAG) PG8_MMA(0, 1, At, B1); PG8_BAR;
;             PG8_LDA(At, 1, 1); PG8_STAGE(PG8_SA(1, 0), a3, voffA);
;             PG8_BAR; PG8_WAIT_L(0); if constexpr (!Epi::DIAG) PG8_MMA(1, 0, At, B0); PG8_BAR; PG8_SCHED;
;             PG8_STAGE(PG8_SB(1, 1), b3 + hstepB, voffB);
;             PG8_WAIT_V(6); PG8_BAR; PG8_MMA(1, 1, At, B1); PG8_BAR;
	s_waitcnt lgkmcnt(0)
	s_waitcnt lgkmcnt(0)
	v_mfma_f32_16x16x32_bf16 v[124:127], v[150:153], v[172:175], v[124:127]
	v_mfma_f32_16x16x32_bf16 v[120:123], v[162:165], v[172:175], v[120:123]
	v_mfma_f32_16x16x32_bf16 v[116:119], v[150:153], v[180:183], v[116:119]
	v_mfma_f32_16x16x32_bf16 v[112:115], v[162:165], v[180:183], v[112:115]
	v_mfma_f32_16x16x32_bf16 v[100:103], v[150:153], v[190:193], v[100:103]
	v_mfma_f32_16x16x32_bf16 v[96:99], v[162:165], v[190:193], v[96:99]
	v_mfma_f32_16x16x32_bf16 v[84:87], v[150:153], v[198:201], v[84:87]
	v_mfma_f32_16x16x32_bf16 v[80:83], v[162:165], v[198:201], v[80:83]
	v_mfma_f32_16x16x32_bf16 v[124:127], v[154:157], v[176:179], v[124:127]
	v_mfma_f32_16x16x32_bf16 v[120:123], v[168:171], v[176:179], v[120:123]
	v_mfma_f32_16x16x32_bf16 v[116:119], v[154:157], v[186:189], v[116:119]
	v_mfma_f32_16x16x32_bf16 v[112:115], v[168:171], v[186:189], v[112:115]
	v_mfma_f32_16x16x32_bf16 v[100:103], v[154:157], v[194:197], v[100:103]
	v_mfma_f32_16x16x32_bf16 v[96:99], v[168:171], v[194:197], v[96:99]
	v_mfma_f32_16x16x32_bf16 v[84:87], v[154:157], v[202:205], v[84:87]
	v_mfma_f32_16x16x32_bf16 v[80:83], v[168:171], v[202:205], v[80:83]
	s_barrier
	s_add_i32 s26, 0, 0x1c000
	s_add_i32 s27, s50, s30
	v_add_u32_e32 v161, s26, v145
	v_lshl_add_u64 v[158:159], v[158:159], 0, s[10:11]
	s_mov_b32 m0, s27
	ds_read_b128 v[206:209], v161
	ds_read_b128 v[210:213], v161 offset:1024
	ds_read_b128 v[214:217], v161 offset:2048
	ds_read_b128 v[218:221], v161 offset:3072
	global_load_lds_dwordx4 v[158:159], off
	v_lshl_add_u64 v[158:159], v[222:223], 0, s[10:11]
	s_add_i32 m0, s27, 0x2000
	s_nop 0
	global_load_lds_dwordx4 v[158:159], off
	s_barrier
	s_waitcnt lgkmcnt(0)
	s_waitcnt lgkmcnt(0)
	v_mfma_f32_16x16x32_bf16 v[108:111], v[206:209], v[172:175], v[108:111]
	v_mfma_f32_16x16x32_bf16 v[104:107], v[214:217], v[172:175], v[104:107]
	v_mfma_f32_16x16x32_bf16 v[92:95], v[206:209], v[180:183], v[92:95]
	v_mfma_f32_16x16x32_bf16 v[88:91], v[214:217], v[180:183], v[88:91]
	v_mfma_f32_16x16x32_bf16 v[76:79], v[206:209], v[190:193], v[76:79]
	v_mfma_f32_16x16x32_bf16 v[72:75], v[214:217], v[190:193], v[72:75]
	v_mfma_f32_16x16x32_bf16 v[68:71], v[206:209], v[198:201], v[68:71]
	v_mfma_f32_16x16x32_bf16 v[64:67], v[214:217], v[198:201], v[64:67]
	v_mfma_f32_16x16x32_bf16 v[108:111], v[210:213], v[176:179], v[108:111]
	v_mfma_f32_16x16x32_bf16 v[104:107], v[218:221], v[176:179], v[104:107]
	v_mfma_f32_16x16x32_bf16 v[92:95], v[210:213], v[186:189], v[92:95]
	v_mfma_f32_16x16x32_bf16 v[88:91], v[218:221], v[186:189], v[88:91]
	v_mfma_f32_16x16x32_bf16 v[76:79], v[210:213], v[194:197], v[76:79]
	v_mfma_f32_16x16x32_bf16 v[72:75], v[218:221], v[194:197], v[72:75]
	v_mfma_f32_16x16x32_bf16 v[68:71], v[210:213], v[202:205], v[68:71]
	v_mfma_f32_16x16x32_bf16 v[64:67], v[218:221], v[202:205], v[64:67]
	s_mov_b32 m0, s39
	v_lshl_add_u64 v[158:159], v[224:225], 0, s[10:11]
	s_barrier
	ds_read_b128 v[172:175], v148 offset:49152
	ds_read_b128 v[176:179], v148 offset:50176
	ds_read_b128 v[180:183], v148 offset:51200
	ds_read_b128 v[186:189], v148 offset:52224
	ds_read_b128 v[190:193], v148 offset:53248
	ds_read_b128 v[194:197], v148 offset:54272
	ds_read_b128 v[198:201], v148 offset:55296
	ds_read_b128 v[202:205], v148 offset:56320
	global_load_lds_dwordx4 v[158:159], off
	v_lshl_add_u64 v[158:159], v[226:227], 0, s[10:11]
	s_mov_b32 m0, s40
	s_nop 0
	global_load_lds_dwordx4 v[158:159], off
	s_barrier
	s_waitcnt lgkmcnt(0)
	s_waitcnt lgkmcnt(0)
	v_mfma_f32_16x16x32_bf16 v[60:63], v[150:153], v[172:175], v[60:63]
	v_mfma_f32_16x16x32_bf16 v[56:59], v[162:165], v[172:175], v[56:59]
	v_mfma_f32_16x16x32_bf16 v[52:55], v[150:153], v[180:183], v[52:55]
	v_mfma_f32_16x16x32_bf16 v[48:51], v[162:165], v[180:183], v[48:51]
	v_mfma_f32_16x16x32_bf16 v[36:39], v[150:153], v[190:193], v[36:39]
	v_mfma_f32_16x16x32_bf16 v[32:35], v[162:165], v[190:193], v[32:35]
	v_mfma_f32_16x16x32_bf16 v[20:23], v[150:153], v[198:201], v[20:23]
	v_mfma_f32_16x16x32_bf16 v[16:19], v[162:165], v[198:201], v[16:19]
	v_mfma_f32_16x16x32_bf16 v[60:63], v[154:157], v[176:179], v[60:63]
	v_mfma_f32_16x16x32_bf16 v[56:59], v[168:171], v[176:179], v[56:59]
	v_mfma_f32_16x16x32_bf16 v[52:55], v[154:157], v[186:189], v[52:55]
	v_mfma_f32_16x16x32_bf16 v[48:51], v[168:171], v[186:189], v[48:51]
	v_mfma_f32_16x16x32_bf16 v[36:39], v[154:157], v[194:197], v[36:39]
	v_mfma_f32_16x16x32_bf16 v[32:35], v[168:171], v[194:197], v[32:35]
	v_mfma_f32_16x16x32_bf16 v[20:23], v[154:157], v[202:205], v[20:23]
	v_mfma_f32_16x16x32_bf16 v[16:19], v[168:171], v[202:205], v[16:19]
	s_barrier
	s_add_u32 s24, s24, 0x80080
	s_addc_u32 s25, s25, 0
	s_add_i32 s26, s26, s30
	v_lshl_add_u64 v[150:151], s[24:25], 0, v[130:131]
	s_mov_b32 m0, s26
	s_nop 0
	global_load_lds_dwordx4 v[150:151], off
	v_lshl_add_u64 v[150:151], s[24:25], 0, v[134:135]
	s_add_i32 m0, s26, 0x2000
	s_nop 0
	global_load_lds_dwordx4 v[150:151], off
	s_waitcnt vmcnt(6)
	s_barrier
; __device__ __forceinline__ unsigned pk2(float lo, float hi) { const f32x2 v = {lo, hi}; const bf16x2_hw b = __builtin_convertvector(v, bf16x2_hw); return __builtin_bit_cast(unsigned, b); }
; #define PG8_MMA(ai, bj, At, Bt) do { __builtin_amdgcn_s_setprio(1); _Pragma("unroll") for (int m = 0; m < 4; ++m) _Pragma("unroll") for (int n = 0; n < 2; ++n) _Pragma("unroll") for (int k = 0; k < 2; ++k) \
;         acc[ai][bj][m][n] = __builtin_amdgcn_mfma_f32_16x16x32_bf16(Bt[n][k], At[m][k], acc[ai][bj][m][n], 0, 0, 0); __builtin_amdgcn_s_setprio(0); } while (0)
; #define PG8_WAIT_V(n) asm volatile("s_waitcnt vmcnt(" #n ")" ::: "memory")
; #define PG8_BAR __builtin_amdgcn_s_barrier()
; template <class Epi, class Sched>
; __device__ __forceinline__ void gemm_phase(LAS unsigned char* lds, const Gemm g, const Sched& S, const Epi& E) {
;     ...
;             PG8_WAIT_V(6); PG8_BAR; PG8_MMA(1, 1, At, B1); PG8_BAR;
;         }
;         E(acc, cur, wr, wc, fr, fq);
;         if (!has_next) break;
;     __device__ __forceinline__ void operator()(const Acc& acc, const Unit& u, int wr, int wc, int fr, int fq) const {
;         const int row0 = u.pm * BM + wr * 64 + fr, col0 = u.pn * BM + wc * 32 + 8 * fq;
; #pragma unroll
;         for (int ai = 0; ai < 2; ++ai)
; #pragma unroll
;             for (int m = 0; m < 4; ++m) { bf16_t* rowp = O + (size_t)(row0 + ai * HALF + m * 16) * ldc + col_off + col0;
; #pragma unroll
;                 for (int bj = 0; bj < 2; ++bj) { f32x4 v0 = acc[ai][bj][m][0], v1 = acc[ai][bj][m][1];
;                     if (scale) { v0 *= *(const f32x4*)(scale + col0 + bj * HALF); v1 *= *(const f32x4*)(scale + col0 + bj * HALF + 4); }
;                     u32x4 w; w.x = pk2(v0[0], v0[1]); w.y = pk2(v0[2], v0[3]); w.z = pk2(v1[0], v1[1]); w.w = pk2(v1[2], v1[3]);
;                     *(u32x4*)(rowp + bj * HALF) = w; }
;                 if (scale) asm volatile("" ::: "memory"); }
	v_mfma_f32_16x16x32_bf16 v[44:47], v[206:209], v[172:175], v[44:47]
	v_mfma_f32_16x16x32_bf16 v[40:43], v[214:217], v[172:175], v[40:43]
	v_mfma_f32_16x16x32_bf16 v[28:31], v[206:209], v[180:183], v[28:31]
	v_mfma_f32_16x16x32_bf16 v[24:27], v[214:217], v[180:183], v[24:27]
	v_mfma_f32_16x16x32_bf16 v[12:15], v[206:209], v[190:193], v[12:15]
	v_mfma_f32_16x16x32_bf16 v[8:11], v[214:217], v[190:193], v[8:11]
	v_mfma_f32_16x16x32_bf16 v[4:7], v[206:209], v[198:201], v[4:7]
	v_mfma_f32_16x16x32_bf16 v[0:3], v[214:217], v[198:201], v[0:3]
	v_mfma_f32_16x16x32_bf16 v[44:47], v[210:213], v[176:179], v[44:47]
	v_mfma_f32_16x16x32_bf16 v[40:43], v[218:221], v[176:179], v[40:43]
	v_mfma_f32_16x16x32_bf16 v[28:31], v[210:213], v[186:189], v[28:31]
	v_mfma_f32_16x16x32_bf16 v[24:27], v[218:221], v[186:189], v[24:27]
	v_mfma_f32_16x16x32_bf16 v[12:15], v[210:213], v[194:197], v[12:15]
	v_mfma_f32_16x16x32_bf16 v[8:11], v[218:221], v[194:197], v[8:11]
	v_mfma_f32_16x16x32_bf16 v[4:7], v[210:213], v[202:205], v[4:7]
	v_mfma_f32_16x16x32_bf16 v[0:3], v[218:221], v[202:205], v[0:3]
	s_add_i32 s49, s49, 2
	s_add_u32 s22, s22, 0x100
	s_addc_u32 s23, s23, 0
	s_add_u32 s47, s47, 0x100
	s_addc_u32 s48, s48, 0
	s_cmp_gt_u32 s49, 29
	s_barrier
	s_cbranch_scc0 .LBB0_475
	s_setprio 0
	v_lshl_add_u32 v156, s12, 8, v144
	v_lshl_or_b32 v150, s44, 8, v146
	v_ashrrev_i32_e32 v151, 31, v150
	v_mov_b64_e32 v[152:153], s[8:9]
	v_cvt_pk_bf16_f32 v68, v68, v69
	v_cvt_pk_bf16_f32 v69, v70, v71
	v_cvt_pk_bf16_f32 v70, v64, v65
	v_add_u32_e32 v64, 0x80, v156
	v_mad_i64_i32 v[154:155], s[22:23], v156, s43, v[152:153]
	v_lshlrev_b64 v[150:151], 1, v[150:151]
	v_cvt_pk_bf16_f32 v108, v108, v109
	v_cvt_pk_bf16_f32 v109, v110, v111
	v_cvt_pk_bf16_f32 v110, v104, v105
	v_or_b32_e32 v104, 16, v156
	v_mad_i64_i32 v[64:65], s[22:23], v64, s43, v[152:153]
	v_cvt_pk_bf16_f32 v44, v44, v45
	v_cvt_pk_bf16_f32 v45, v46, v47
	v_cvt_pk_bf16_f32 v46, v40, v41
	v_add_u32_e32 v40, 0x90, v156
	v_lshl_add_u64 v[154:155], v[154:155], 0, v[150:151]
	v_cvt_pk_bf16_f32 v111, v106, v107
	v_mad_i64_i32 v[104:105], s[22:23], v104, s43, v[152:153]
	v_cvt_pk_bf16_f32 v92, v92, v93
	v_cvt_pk_bf16_f32 v93, v94, v95
	v_cvt_pk_bf16_f32 v94, v88, v89
	v_or_b32_e32 v88, 32, v156
	v_lshl_add_u64 v[64:65], v[64:65], 0, v[150:151]
	v_cvt_pk_bf16_f32 v47, v42, v43
	v_mad_i64_i32 v[40:41], s[22:23], v40, s43, v[152:153]
	v_cvt_pk_bf16_f32 v28, v28, v29
	v_cvt_pk_bf16_f32 v29, v30, v31
	v_cvt_pk_bf16_f32 v30, v24, v25
	v_add_u32_e32 v24, 0xa0, v156
	global_store_dwordx4 v[154:155], v[108:111], off offset:256
	v_cvt_pk_bf16_f32 v95, v90, v91
	v_mad_i64_i32 v[88:89], s[22:23], v88, s43, v[152:153]
	v_lshl_add_u64 v[108:109], v[104:105], 0, v[150:151]
	v_cvt_pk_bf16_f32 v76, v76, v77
	v_cvt_pk_bf16_f32 v77, v78, v79
	v_cvt_pk_bf16_f32 v78, v72, v73
	v_or_b32_e32 v72, 48, v156
	global_store_dwordx4 v[64:65], v[44:47], off offset:256
	v_cvt_pk_bf16_f32 v31, v26, v27
	v_mad_i64_i32 v[24:25], s[22:23], v24, s43, v[152:153]
	v_lshl_add_u64 v[44:45], v[40:41], 0, v[150:151]
	v_cvt_pk_bf16_f32 v12, v12, v13
	v_cvt_pk_bf16_f32 v13, v14, v15
	v_cvt_pk_bf16_f32 v14, v8, v9
	v_add_u32_e32 v8, 0xb0, v156
	global_store_dwordx4 v[108:109], v[92:95], off offset:256
	v_cvt_pk_bf16_f32 v79, v74, v75
	v_mad_i64_i32 v[72:73], s[22:23], v72, s43, v[152:153]
	v_lshl_add_u64 v[92:93], v[88:89], 0, v[150:151]
	global_store_dwordx4 v[44:45], v[28:31], off offset:256
	v_cvt_pk_bf16_f32 v15, v10, v11
	v_mad_i64_i32 v[8:9], s[22:23], v8, s43, v[152:153]
	v_lshl_add_u64 v[28:29], v[24:25], 0, v[150:151]
	v_cvt_pk_bf16_f32 v124, v124, v125
	v_cvt_pk_bf16_f32 v125, v126, v127
	v_cvt_pk_bf16_f32 v126, v120, v121
	v_cvt_pk_bf16_f32 v127, v122, v123
	v_cvt_pk_bf16_f32 v104, v116, v117
	v_cvt_pk_bf16_f32 v105, v118, v119
	v_cvt_pk_bf16_f32 v106, v112, v113
	v_cvt_pk_bf16_f32 v107, v114, v115
	v_cvt_pk_bf16_f32 v88, v100, v101
	v_cvt_pk_bf16_f32 v89, v102, v103
	v_cvt_pk_bf16_f32 v90, v96, v97
	v_cvt_pk_bf16_f32 v91, v98, v99
	global_store_dwordx4 v[92:93], v[76:79], off offset:256
	v_cvt_pk_bf16_f32 v74, v80, v81
	v_cvt_pk_bf16_f32 v75, v82, v83
	v_lshl_add_u64 v[76:77], v[72:73], 0, v[150:151]
	v_cvt_pk_bf16_f32 v72, v84, v85
	v_cvt_pk_bf16_f32 v73, v86, v87
	v_cvt_pk_bf16_f32 v71, v66, v67
	v_cvt_pk_bf16_f32 v60, v60, v61
	v_cvt_pk_bf16_f32 v61, v62, v63
	v_cvt_pk_bf16_f32 v62, v56, v57
	v_cvt_pk_bf16_f32 v63, v58, v59
	v_cvt_pk_bf16_f32 v40, v52, v53
	v_cvt_pk_bf16_f32 v41, v54, v55
	v_cvt_pk_bf16_f32 v42, v48, v49
	v_cvt_pk_bf16_f32 v43, v50, v51
	v_cvt_pk_bf16_f32 v24, v36, v37
	v_cvt_pk_bf16_f32 v25, v38, v39
	v_cvt_pk_bf16_f32 v26, v32, v33
	v_cvt_pk_bf16_f32 v27, v34, v35
	global_store_dwordx4 v[28:29], v[12:15], off offset:256
	v_cvt_pk_bf16_f32 v10, v16, v17
	v_cvt_pk_bf16_f32 v11, v18, v19
	v_lshl_add_u64 v[12:13], v[8:9], 0, v[150:151]
	v_cvt_pk_bf16_f32 v8, v20, v21
	v_cvt_pk_bf16_f32 v9, v22, v23
	v_cvt_pk_bf16_f32 v4, v4, v5
	v_cvt_pk_bf16_f32 v5, v6, v7
	v_cvt_pk_bf16_f32 v6, v0, v1
	v_cvt_pk_bf16_f32 v7, v2, v3
	s_and_b64 vcc, exec, s[6:7]
	s_mov_b32 s44, s14
	s_mov_b32 s12, s16
	s_mov_b64 s[24:25], s[20:21]
	s_mov_b64 s[22:23], s[18:19]
	global_store_dwordx4 v[154:155], v[124:127], off
	global_store_dwordx4 v[108:109], v[104:107], off
	global_store_dwordx4 v[92:93], v[88:91], off
	global_store_dwordx4 v[76:77], v[72:75], off
	global_store_dwordx4 v[76:77], v[68:71], off offset:256
	global_store_dwordx4 v[64:65], v[60:63], off
	global_store_dwordx4 v[44:45], v[40:43], off
	global_store_dwordx4 v[28:29], v[24:27], off
	global_store_dwordx4 v[12:13], v[8:11], off
	global_store_dwordx4 v[12:13], v[4:7], off offset:256
	s_cbranch_vccz .LBB0_468
	s_waitcnt vmcnt(0)
	s_cmpk_gt_u32 s3, 0xff
	s_cbranch_scc1 .LBB0_479
	s_barrier

; #define PG8_STAGE(bufoff, gbase, voff) do { _Pragma("unroll") for (int _i = 0; _i < 2; ++_i) \
;         __builtin_amdgcn_global_load_lds((const unsigned*)((const char*)(gbase) + (voff)[_i]), (LAS unsigned*)(lds + (bufoff) + ldsw + _i * 8192), 16, 0, 0); } while (0)
; #define PG8_LDA(dst, b, h) do { _Pragma("unroll") for (int m = 0; m < 4; ++m) _Pragma("unroll") for (int k = 0; k < 2; ++k) dst[m][k] = *(const LAS bf16x8*)(lds + PG8_SA(b, h) + aoff + m * 2048 + k * 1024); } while (0)
; #define PG8_LDB(dst, b, h) do { _Pragma("unroll") for (int n = 0; n < 2; ++n) _Pragma("unroll") for (int k = 0; k < 2; ++k) dst[n][k] = *(const LAS bf16x8*)(lds + PG8_SB(b, h) + boff + n * 2048 + k * 1024); } while (0)
; #define PG8_MMA(ai, bj, At, Bt) do { __builtin_amdgcn_s_setprio(1); _Pragma("unroll") for (int m = 0; m < 4; ++m) _Pragma("unroll") for (int n = 0; n < 2; ++n) _Pragma("unroll") for (int k = 0; k < 2; ++k) \
;         acc[ai][bj][m][n] = __builtin_amdgcn_mfma_f32_16x16x32_bf16(Bt[n][k], At[m][k], acc[ai][bj][m][n], 0, 0, 0); __builtin_amdgcn_s_setprio(0); } while (0)
; #define PG8_WAIT_L(n) asm volatile("s_waitcnt lgkmcnt(" #n ")" ::: "memory")
; #define PG8_BAR __builtin_amdgcn_s_barrier()
; #define PG8_SCHED __builtin_amdgcn_sched_barrier(0)
; template <class Epi, class Sched>
; __device__ __forceinline__ void gemm_phase(LAS unsigned char* lds, const Gemm g, const Sched& S, const Epi& E) {
;     ...
;         for (int t = 0; t < nt; t += 2) {
;             const bool last = (t == nt - 2);
;             const char* a1 = cA + (size_t)(t + 1) * kstep;
;             const char* a2 = last ? nA : cA + (size_t)(t + 2) * kstep; const char* b2 = last ? nB : cB + (size_t)(t + 2) * kstep;
;             const char* a3 = a2 + kstep; const char* b3 = b2 + kstep;
;             PG8_LDB(B0, 0, 0); PG8_SCHED; PG8_LDA(At, 0, 0); PG8_STAGE(PG8_SA(1, 1), a1 + hstepA, voffA);
;             PG8_WAIT_L(8); PG8_BAR; PG8_WAIT_L(0); PG8_MMA(0, 0, At, B0); PG8_BAR; PG8_SCHED;
;     ...
;         for (int a = 0; a < 2; ++a)
; #pragma unroll
;             for (int b = 0; b < 2; ++b)
; #pragma unroll
;                 for (int m = 0; m < 4; ++m)
; #pragma unroll
;                     for (int n = 0; n < 2; ++n) acc[a][b][m][n] = (f32x4){0.f, 0.f, 0.f, 0.f};
;         cur = nxt; cA = nA; cB = nB; ++ui;
.LBB0_1842:
	s_ashr_i32 s15, s14, 31
	v_cmp_lt_i64_e32 vcc, s[16:17], v[140:141]
	s_lshl_b64 s[16:17], s[14:15], 20
	s_add_u32 s16, s28, s16
	s_addc_u32 s17, s29, s17
	s_and_b64 s[18:19], vcc, exec
	s_cselect_b32 s15, s17, s23
	s_cselect_b32 s48, s16, s22
	s_ashr_i32 s13, s12, 31
	s_lshl_b64 s[18:19], s[12:13], 20
	s_add_u32 s18, s30, s18
	s_addc_u32 s19, s31, s19
	s_and_b64 s[26:27], vcc, exec
	s_cselect_b32 s13, s19, s25
	s_cselect_b32 s49, s18, s24
	s_add_u32 s22, s22, 0x80080
	s_addc_u32 s23, s23, 0
	s_add_u32 s50, s24, 0x100
	v_mov_b32_e32 v0, 0
	s_addc_u32 s51, s25, 0
	s_mov_b32 s52, -2
	v_mov_b32_e32 v1, v0
	v_mov_b32_e32 v2, v0
	v_mov_b32_e32 v3, v0
	v_mov_b32_e32 v8, v0
	v_mov_b32_e32 v9, v0
	v_mov_b32_e32 v10, v0
	v_mov_b32_e32 v11, v0
	v_mov_b32_e32 v16, v0
	v_mov_b32_e32 v17, v0
	v_mov_b32_e32 v18, v0
	v_mov_b32_e32 v19, v0
	v_mov_b32_e32 v24, v0
	v_mov_b32_e32 v25, v0
	v_mov_b32_e32 v26, v0
	v_mov_b32_e32 v27, v0
	v_mov_b32_e32 v32, v0
	v_mov_b32_e32 v33, v0
	v_mov_b32_e32 v34, v0
	v_mov_b32_e32 v35, v0
	v_mov_b32_e32 v40, v0
	v_mov_b32_e32 v41, v0
	v_mov_b32_e32 v42, v0
	v_mov_b32_e32 v43, v0
	v_mov_b32_e32 v48, v0
	v_mov_b32_e32 v49, v0
	v_mov_b32_e32 v50, v0
	v_mov_b32_e32 v51, v0
	v_mov_b32_e32 v56, v0
	v_mov_b32_e32 v57, v0
	v_mov_b32_e32 v58, v0
	v_mov_b32_e32 v59, v0
	v_mov_b32_e32 v4, v0
	v_mov_b32_e32 v5, v0
	v_mov_b32_e32 v6, v0
	v_mov_b32_e32 v7, v0
	v_mov_b32_e32 v12, v0
	v_mov_b32_e32 v13, v0
	v_mov_b32_e32 v14, v0
	v_mov_b32_e32 v15, v0
	v_mov_b32_e32 v20, v0
	v_mov_b32_e32 v21, v0
	v_mov_b32_e32 v22, v0
	v_mov_b32_e32 v23, v0
	v_mov_b32_e32 v28, v0
	v_mov_b32_e32 v29, v0
	v_mov_b32_e32 v30, v0
	v_mov_b32_e32 v31, v0
	v_mov_b32_e32 v36, v0
	v_mov_b32_e32 v37, v0
	v_mov_b32_e32 v38, v0
	v_mov_b32_e32 v39, v0
	v_mov_b32_e32 v44, v0
	v_mov_b32_e32 v45, v0
	v_mov_b32_e32 v46, v0
	v_mov_b32_e32 v47, v0
	v_mov_b32_e32 v52, v0
	v_mov_b32_e32 v53, v0
	v_mov_b32_e32 v54, v0
	v_mov_b32_e32 v55, v0
	v_mov_b32_e32 v60, v0
	v_mov_b32_e32 v61, v0
	v_mov_b32_e32 v62, v0
	v_mov_b32_e32 v63, v0
	v_mov_b32_e32 v64, v0
	v_mov_b32_e32 v65, v0
	v_mov_b32_e32 v66, v0
	v_mov_b32_e32 v67, v0
	v_mov_b32_e32 v72, v0
	v_mov_b32_e32 v73, v0
	v_mov_b32_e32 v74, v0
	v_mov_b32_e32 v75, v0
	v_mov_b32_e32 v80, v0
	v_mov_b32_e32 v81, v0
	v_mov_b32_e32 v82, v0
	v_mov_b32_e32 v83, v0
	v_mov_b32_e32 v88, v0
	v_mov_b32_e32 v89, v0
	v_mov_b32_e32 v90, v0
	v_mov_b32_e32 v91, v0
	v_mov_b32_e32 v96, v0
	v_mov_b32_e32 v97, v0
	v_mov_b32_e32 v98, v0
	v_mov_b32_e32 v99, v0
	v_mov_b32_e32 v104, v0
	v_mov_b32_e32 v105, v0
	v_mov_b32_e32 v106, v0
	v_mov_b32_e32 v107, v0
	v_mov_b32_e32 v112, v0
	v_mov_b32_e32 v113, v0
	v_mov_b32_e32 v114, v0
	v_mov_b32_e32 v115, v0
	v_mov_b32_e32 v120, v0
	v_mov_b32_e32 v121, v0
	v_mov_b32_e32 v122, v0
	v_mov_b32_e32 v123, v0
	v_mov_b32_e32 v68, v0
	v_mov_b32_e32 v69, v0
	v_mov_b32_e32 v70, v0
	v_mov_b32_e32 v71, v0
	v_mov_b32_e32 v76, v0
	v_mov_b32_e32 v77, v0
	v_mov_b32_e32 v78, v0
	v_mov_b32_e32 v79, v0
	v_mov_b32_e32 v84, v0
	v_mov_b32_e32 v85, v0
	v_mov_b32_e32 v86, v0
	v_mov_b32_e32 v87, v0
	v_mov_b32_e32 v92, v0
	v_mov_b32_e32 v93, v0
	v_mov_b32_e32 v94, v0
	v_mov_b32_e32 v95, v0
	v_mov_b32_e32 v100, v0
	v_mov_b32_e32 v101, v0
	v_mov_b32_e32 v102, v0
	v_mov_b32_e32 v103, v0
	v_mov_b32_e32 v108, v0
	v_mov_b32_e32 v109, v0
	v_mov_b32_e32 v110, v0
	v_mov_b32_e32 v111, v0
	v_mov_b32_e32 v116, v0
	v_mov_b32_e32 v117, v0
	v_mov_b32_e32 v118, v0
	v_mov_b32_e32 v119, v0
	v_mov_b32_e32 v124, v0
	v_mov_b32_e32 v125, v0
	v_mov_b32_e32 v126, v0
	v_mov_b32_e32 v127, v0
	s_lshr_b32 s57, s3, 8
	s_cmp_lg_u32 s57, 0
	s_cbranch_scc0 .Lprio_1843
	s_setprio 1
.Lprio_1843:
.LBB0_1843:
	ds_read_b128 v[150:153], v147
	ds_read_b128 v[154:157], v147 offset:1024
	ds_read_b128 v[162:165], v147 offset:2048
	ds_read_b128 v[166:169], v147 offset:3072
	s_add_u32 s24, s22, 0xfff80080
	s_addc_u32 s25, s23, -1
	s_cmp_eq_u32 s52, 28
	s_cselect_b32 s27, s15, s25
	s_cselect_b32 s26, s48, s24
	s_cselect_b32 s25, s13, s51
	s_cselect_b32 s24, s49, s50
	v_lshl_add_u64 v[158:159], s[22:23], 0, v[136:137]
	s_add_i32 m0, s21, 0xc000
	ds_read_b128 v[170:173], v148
	ds_read_b128 v[174:177], v148 offset:1024
	ds_read_b128 v[178:181], v148 offset:2048
	ds_read_b128 v[186:189], v148 offset:3072
	ds_read_b128 v[190:193], v148 offset:4096
	ds_read_b128 v[194:197], v148 offset:5120
	ds_read_b128 v[198:201], v148 offset:6144
	ds_read_b128 v[202:205], v148 offset:7168
	global_load_lds_dwordx4 v[158:159], off
	v_lshl_add_u64 v[158:159], s[22:23], 0, v[138:139]
	s_add_i32 m0, s21, 0xe000
	s_nop 0
	global_load_lds_dwordx4 v[158:159], off
	s_waitcnt lgkmcnt(8)
	s_barrier
	s_waitcnt lgkmcnt(0)
	s_waitcnt lgkmcnt(0)
	v_mfma_f32_16x16x32_bf16 v[124:127], v[150:153], v[170:173], v[124:127]
	v_mfma_f32_16x16x32_bf16 v[116:119], v[162:165], v[170:173], v[116:119]
	v_mfma_f32_16x16x32_bf16 v[108:111], v[150:153], v[178:181], v[108:111]
	v_mfma_f32_16x16x32_bf16 v[100:103], v[162:165], v[178:181], v[100:103]
	v_mfma_f32_16x16x32_bf16 v[92:95], v[150:153], v[190:193], v[92:95]
	v_mfma_f32_16x16x32_bf16 v[84:87], v[162:165], v[190:193], v[84:87]
	v_mfma_f32_16x16x32_bf16 v[76:79], v[150:153], v[198:201], v[76:79]
	v_mfma_f32_16x16x32_bf16 v[68:71], v[162:165], v[198:201], v[68:71]
	v_mfma_f32_16x16x32_bf16 v[124:127], v[154:157], v[174:177], v[124:127]
	v_mfma_f32_16x16x32_bf16 v[116:119], v[166:169], v[174:177], v[116:119]
	v_mfma_f32_16x16x32_bf16 v[108:111], v[154:157], v[186:189], v[108:111]
	v_mfma_f32_16x16x32_bf16 v[100:103], v[166:169], v[186:189], v[100:103]
	v_mfma_f32_16x16x32_bf16 v[92:95], v[154:157], v[194:197], v[92:95]
	v_mfma_f32_16x16x32_bf16 v[84:87], v[166:169], v[194:197], v[84:87]
	v_mfma_f32_16x16x32_bf16 v[76:79], v[154:157], v[202:205], v[76:79]
	v_mfma_f32_16x16x32_bf16 v[68:71], v[166:169], v[202:205], v[68:71]
	s_barrier
; #define PG8_STAGE(bufoff, gbase, voff) do { _Pragma("unroll") for (int _i = 0; _i < 2; ++_i) \
;         __builtin_amdgcn_global_load_lds((const unsigned*)((const char*)(gbase) + (voff)[_i]), (LAS unsigned*)(lds + (bufoff) + ldsw + _i * 8192), 16, 0, 0); } while (0)
; #define PG8_LDA(dst, b, h) do { _Pragma("unroll") for (int m = 0; m < 4; ++m) _Pragma("unroll") for (int k = 0; k < 2; ++k) dst[m][k] = *(const LAS bf16x8*)(lds + PG8_SA(b, h) + aoff + m * 2048 + k * 1024); } while (0)
; #define PG8_LDB(dst, b, h) do { _Pragma("unroll") for (int n = 0; n < 2; ++n) _Pragma("unroll") for (int k = 0; k < 2; ++k) dst[n][k] = *(const LAS bf16x8*)(lds + PG8_SB(b, h) + boff + n * 2048 + k * 1024); } while (0)
; #define PG8_MMA(ai, bj, At, Bt) do { __builtin_amdgcn_s_setprio(1); _Pragma("unroll") for (int m = 0; m < 4; ++m) _Pragma("unroll") for (int n = 0; n < 2; ++n) _Pragma("unroll") for (int k = 0; k < 2; ++k) \
;         acc[ai][bj][m][n] = __builtin_amdgcn_mfma_f32_16x16x32_bf16(Bt[n][k], At[m][k], acc[ai][bj][m][n], 0, 0, 0); __builtin_amdgcn_s_setprio(0); } while (0)
; #define PG8_WAIT_V(n) asm volatile("s_waitcnt vmcnt(" #n ")" ::: "memory")
; #define PG8_WAIT_L(n) asm volatile("s_waitcnt lgkmcnt(" #n ")" ::: "memory")
; #define PG8_BAR __builtin_amdgcn_s_barrier()
; #define PG8_SCHED __builtin_amdgcn_sched_barrier(0)
; template <class Epi, class Sched>
; __device__ __forceinline__ void gemm_phase(LAS unsigned char* lds, const Gemm g, const Sched& S, const Epi& E) {
;     ...
;             PG8_LDB(B1, 0, 1); PG8_STAGE(PG8_SB(0, 0), b2, voffB);
;             PG8_BAR; PG8_WAIT_L(0); if constexpr (!Epi::DIAG) PG8_MMA(0, 1, At, B1); PG8_BAR;
;             PG8_LDA(At, 0, 1); PG8_STAGE(PG8_SA(0, 0), a2, voffA);
;             PG8_BAR; PG8_WAIT_L(0); if constexpr (!Epi::DIAG) PG8_MMA(1, 0, At, B0); PG8_BAR; PG8_SCHED;
;             PG8_STAGE(PG8_SB(0, 1), b2 + hstepB, voffB);
;             PG8_WAIT_V(6); PG8_BAR; PG8_MMA(1, 1, At, B1); PG8_BAR;
;             PG8_LDB(B0, 1, 0); PG8_SCHED; PG8_LDA(At, 1, 0); PG8_STAGE(PG8_SA(0, 1), a2 + hstepA, voffA);
;             PG8_WAIT_L(8); PG8_BAR; PG8_WAIT_L(0); PG8_MMA(0, 0, At, B0); PG8_BAR; PG8_SCHED;
	s_add_i32 s53, s44, s34
	v_lshl_add_u64 v[158:159], s[24:25], 0, v[130:131]
	s_mov_b32 m0, s53
	ds_read_b128 v[206:209], v149
	ds_read_b128 v[210:213], v149 offset:1024
	ds_read_b128 v[214:217], v149 offset:2048
	ds_read_b128 v[218:221], v149 offset:3072
	global_load_lds_dwordx4 v[158:159], off
	v_lshl_add_u64 v[182:183], s[24:25], 0, v[134:135]
	s_add_i32 m0, s53, 0x2000
	s_nop 0
	global_load_lds_dwordx4 v[182:183], off
	s_barrier
	s_waitcnt lgkmcnt(0)
	s_waitcnt lgkmcnt(0)
	v_mfma_f32_16x16x32_bf16 v[120:123], v[206:209], v[170:173], v[120:123]
	v_mfma_f32_16x16x32_bf16 v[112:115], v[214:217], v[170:173], v[112:115]
	v_mfma_f32_16x16x32_bf16 v[104:107], v[206:209], v[178:181], v[104:107]
	v_mfma_f32_16x16x32_bf16 v[96:99], v[214:217], v[178:181], v[96:99]
	v_mfma_f32_16x16x32_bf16 v[88:91], v[206:209], v[190:193], v[88:91]
	v_mfma_f32_16x16x32_bf16 v[80:83], v[214:217], v[190:193], v[80:83]
	v_mfma_f32_16x16x32_bf16 v[72:75], v[206:209], v[198:201], v[72:75]
	v_mfma_f32_16x16x32_bf16 v[64:67], v[214:217], v[198:201], v[64:67]
	v_mfma_f32_16x16x32_bf16 v[120:123], v[210:213], v[174:177], v[120:123]
	v_mfma_f32_16x16x32_bf16 v[112:115], v[218:221], v[174:177], v[112:115]
	v_mfma_f32_16x16x32_bf16 v[104:107], v[210:213], v[186:189], v[104:107]
	v_mfma_f32_16x16x32_bf16 v[96:99], v[218:221], v[186:189], v[96:99]
	v_mfma_f32_16x16x32_bf16 v[88:91], v[210:213], v[194:197], v[88:91]
	v_mfma_f32_16x16x32_bf16 v[80:83], v[218:221], v[194:197], v[80:83]
	v_mfma_f32_16x16x32_bf16 v[72:75], v[210:213], v[202:205], v[72:75]
	v_mfma_f32_16x16x32_bf16 v[64:67], v[218:221], v[202:205], v[64:67]
	s_mov_b32 m0, s21
	v_lshl_add_u64 v[222:223], s[26:27], 0, v[128:129]
	s_barrier
	ds_read_b128 v[170:173], v148 offset:16384
	ds_read_b128 v[174:177], v148 offset:17408
	ds_read_b128 v[178:181], v148 offset:18432
	ds_read_b128 v[186:189], v148 offset:19456
	ds_read_b128 v[190:193], v148 offset:20480
	ds_read_b128 v[194:197], v148 offset:21504
	ds_read_b128 v[198:201], v148 offset:22528
	ds_read_b128 v[202:205], v148 offset:23552
	global_load_lds_dwordx4 v[222:223], off
	v_lshl_add_u64 v[224:225], s[26:27], 0, v[132:133]
	s_mov_b32 m0, s37
	s_nop 0
	global_load_lds_dwordx4 v[224:225], off
	s_barrier
	s_waitcnt lgkmcnt(0)
	s_waitcnt lgkmcnt(0)
	v_mfma_f32_16x16x32_bf16 v[60:63], v[150:153], v[170:173], v[60:63]
	v_mfma_f32_16x16x32_bf16 v[52:55], v[162:165], v[170:173], v[52:55]
	v_mfma_f32_16x16x32_bf16 v[44:47], v[150:153], v[178:181], v[44:47]
	v_mfma_f32_16x16x32_bf16 v[36:39], v[162:165], v[178:181], v[36:39]
	v_mfma_f32_16x16x32_bf16 v[28:31], v[150:153], v[190:193], v[28:31]
	v_mfma_f32_16x16x32_bf16 v[20:23], v[162:165], v[190:193], v[20:23]
	v_mfma_f32_16x16x32_bf16 v[12:15], v[150:153], v[198:201], v[12:15]
	v_mfma_f32_16x16x32_bf16 v[4:7], v[162:165], v[198:201], v[4:7]
	v_mfma_f32_16x16x32_bf16 v[60:63], v[154:157], v[174:177], v[60:63]
	v_mfma_f32_16x16x32_bf16 v[52:55], v[166:169], v[174:177], v[52:55]
	v_mfma_f32_16x16x32_bf16 v[44:47], v[154:157], v[186:189], v[44:47]
	v_mfma_f32_16x16x32_bf16 v[36:39], v[166:169], v[186:189], v[36:39]
	v_mfma_f32_16x16x32_bf16 v[28:31], v[154:157], v[194:197], v[28:31]
	v_mfma_f32_16x16x32_bf16 v[20:23], v[166:169], v[194:197], v[20:23]
	v_mfma_f32_16x16x32_bf16 v[12:15], v[154:157], v[202:205], v[12:15]
	v_mfma_f32_16x16x32_bf16 v[4:7], v[166:169], v[202:205], v[4:7]
	s_barrier
	s_add_u32 s54, s24, 0x80000
	s_addc_u32 s55, s25, 0
	s_add_i32 s53, s45, s34
	v_lshl_add_u64 v[150:151], s[54:55], 0, v[130:131]
	s_mov_b32 m0, s53
	s_nop 0
	global_load_lds_dwordx4 v[150:151], off
	v_lshl_add_u64 v[150:151], s[54:55], 0, v[134:135]
	s_add_i32 m0, s53, 0x2000
	s_nop 0
	global_load_lds_dwordx4 v[150:151], off
	s_waitcnt vmcnt(6)
	s_barrier
	v_mfma_f32_16x16x32_bf16 v[56:59], v[206:209], v[170:173], v[56:59]
	v_mfma_f32_16x16x32_bf16 v[48:51], v[214:217], v[170:173], v[48:51]
	v_mfma_f32_16x16x32_bf16 v[40:43], v[206:209], v[178:181], v[40:43]
	v_mfma_f32_16x16x32_bf16 v[32:35], v[214:217], v[178:181], v[32:35]
	v_mfma_f32_16x16x32_bf16 v[24:27], v[206:209], v[190:193], v[24:27]
	v_mfma_f32_16x16x32_bf16 v[16:19], v[214:217], v[190:193], v[16:19]
	v_mfma_f32_16x16x32_bf16 v[8:11], v[206:209], v[198:201], v[8:11]
	v_mfma_f32_16x16x32_bf16 v[0:3], v[214:217], v[198:201], v[0:3]
	v_mfma_f32_16x16x32_bf16 v[56:59], v[210:213], v[174:177], v[56:59]
	v_mfma_f32_16x16x32_bf16 v[48:51], v[218:221], v[174:177], v[48:51]
	v_mfma_f32_16x16x32_bf16 v[40:43], v[210:213], v[186:189], v[40:43]
	v_mfma_f32_16x16x32_bf16 v[32:35], v[218:221], v[186:189], v[32:35]
	v_mfma_f32_16x16x32_bf16 v[24:27], v[210:213], v[194:197], v[24:27]
	v_mfma_f32_16x16x32_bf16 v[16:19], v[218:221], v[194:197], v[16:19]
	v_mfma_f32_16x16x32_bf16 v[8:11], v[210:213], v[202:205], v[8:11]
	v_mfma_f32_16x16x32_bf16 v[0:3], v[218:221], v[202:205], v[0:3]
	s_add_i32 s53, 0, 0x18000
	v_add_u32_e32 v161, s53, v145
	s_barrier
	ds_read_b128 v[150:153], v161
	ds_read_b128 v[154:157], v161 offset:1024
	ds_read_b128 v[162:165], v161 offset:2048
	ds_read_b128 v[166:169], v161 offset:3072
	s_add_u32 s26, s26, 0x80000
	s_addc_u32 s27, s27, 0
	s_mov_b32 m0, s38
	v_lshl_add_u64 v[206:207], s[26:27], 0, v[128:129]
	ds_read_b128 v[170:173], v148 offset:32768
	ds_read_b128 v[174:177], v148 offset:33792
	ds_read_b128 v[178:181], v148 offset:34816
	ds_read_b128 v[186:189], v148 offset:35840
	ds_read_b128 v[190:193], v148 offset:36864
	ds_read_b128 v[194:197], v148 offset:37888
	ds_read_b128 v[198:201], v148 offset:38912
	ds_read_b128 v[202:205], v148 offset:39936
	global_load_lds_dwordx4 v[206:207], off
	v_lshl_add_u64 v[206:207], s[26:27], 0, v[132:133]
	s_mov_b32 m0, s39
	s_nop 0
	global_load_lds_dwordx4 v[206:207], off
	s_waitcnt lgkmcnt(8)
	s_barrier
; #define PG8_STAGE(bufoff, gbase, voff) do { _Pragma("unroll") for (int _i = 0; _i < 2; ++_i) \
;         __builtin_amdgcn_global_load_lds((const unsigned*)((const char*)(gbase) + (voff)[_i]), (LAS unsigned*)(lds + (bufoff) + ldsw + _i * 8192), 16, 0, 0); } while (0)
; #define PG8_LDA(dst, b, h) do { _Pragma("unroll") for (int m = 0; m < 4; ++m) _Pragma("unroll") for (int k = 0; k < 2; ++k) dst[m][k] = *(const LAS bf16x8*)(lds + PG8_SA(b, h) + aoff + m * 2048 + k * 1024); } while (0)
; #define PG8_LDB(dst, b, h) do { _Pragma("unroll") for (int n = 0; n < 2; ++n) _Pragma("unroll") for (int k = 0; k < 2; ++k) dst[n][k] = *(const LAS bf16x8*)(lds + PG8_SB(b, h) + boff + n * 2048 + k * 1024); } while (0)
; #define PG8_MMA(ai, bj, At, Bt) do { __builtin_amdgcn_s_setprio(1); _Pragma("unroll") for (int m = 0; m < 4; ++m) _Pragma("unroll") for (int n = 0; n < 2; ++n) _Pragma("unroll") for (int k = 0; k < 2; ++k) \
;         acc[ai][bj][m][n] = __builtin_amdgcn_mfma_f32_16x16x32_bf16(Bt[n][k], At[m][k], acc[ai][bj][m][n], 0, 0, 0); __builtin_amdgcn_s_setprio(0); } while (0)
; #define PG8_WAIT_V(n) asm volatile("s_waitcnt vmcnt(" #n ")" ::: "memory")
; #define PG8_WAIT_L(n) asm volatile("s_waitcnt lgkmcnt(" #n ")" ::: "memory")
; #define PG8_BAR __builtin_amdgcn_s_barrier()
; #define PG8_SCHED __builtin_amdgcn_sched_barrier(0)
; template <class Epi, class Sched>
; __device__ __forceinline__ void gemm_phase(LAS unsigned char* lds, const Gemm g, const Sched& S, const Epi& E) {
;     ...
;             PG8_WAIT_L(8); PG8_BAR; PG8_WAIT_L(0); PG8_MMA(0, 0, At, B0); PG8_BAR; PG8_SCHED;
;             PG8_LDB(B1, 1, 1); PG8_STAGE(PG8_SB(1, 0), b3, voffB);
;             PG8_BAR; PG8_WAIT_L(0); if constexpr (!Epi::DIAG) PG8_MMA(0, 1, At, B1); PG8_BAR;
;             PG8_LDA(At, 1, 1); PG8_STAGE(PG8_SA(1, 0), a3, voffA);
;             PG8_BAR; PG8_WAIT_L(0); if constexpr (!Epi::DIAG) PG8_MMA(1, 0, At, B0); PG8_BAR; PG8_SCHED;
;             PG8_STAGE(PG8_SB(1, 1), b3 + hstepB, voffB);
;             PG8_WAIT_V(6); PG8_BAR; PG8_MMA(1, 1, At, B1); PG8_BAR;
	s_waitcnt lgkmcnt(0)
	s_waitcnt lgkmcnt(0)
	v_mfma_f32_16x16x32_bf16 v[124:127], v[150:153], v[170:173], v[124:127]
	v_mfma_f32_16x16x32_bf16 v[116:119], v[162:165], v[170:173], v[116:119]
	v_mfma_f32_16x16x32_bf16 v[108:111], v[150:153], v[178:181], v[108:111]
	v_mfma_f32_16x16x32_bf16 v[100:103], v[162:165], v[178:181], v[100:103]
	v_mfma_f32_16x16x32_bf16 v[92:95], v[150:153], v[190:193], v[92:95]
	v_mfma_f32_16x16x32_bf16 v[84:87], v[162:165], v[190:193], v[84:87]
	v_mfma_f32_16x16x32_bf16 v[76:79], v[150:153], v[198:201], v[76:79]
	v_mfma_f32_16x16x32_bf16 v[68:71], v[162:165], v[198:201], v[68:71]
	v_mfma_f32_16x16x32_bf16 v[124:127], v[154:157], v[174:177], v[124:127]
	v_mfma_f32_16x16x32_bf16 v[116:119], v[166:169], v[174:177], v[116:119]
	v_mfma_f32_16x16x32_bf16 v[108:111], v[154:157], v[186:189], v[108:111]
	v_mfma_f32_16x16x32_bf16 v[100:103], v[166:169], v[186:189], v[100:103]
	v_mfma_f32_16x16x32_bf16 v[92:95], v[154:157], v[194:197], v[92:95]
	v_mfma_f32_16x16x32_bf16 v[84:87], v[166:169], v[194:197], v[84:87]
	v_mfma_f32_16x16x32_bf16 v[76:79], v[154:157], v[202:205], v[76:79]
	v_mfma_f32_16x16x32_bf16 v[68:71], v[166:169], v[202:205], v[68:71]
	s_barrier
	s_add_i32 s26, 0, 0x1c000
	s_add_i32 s27, s53, s34
	v_add_u32_e32 v161, s26, v145
	v_lshl_add_u64 v[158:159], v[158:159], 0, s[10:11]
	s_mov_b32 m0, s27
	ds_read_b128 v[206:209], v161
	ds_read_b128 v[210:213], v161 offset:1024
	ds_read_b128 v[214:217], v161 offset:2048
	ds_read_b128 v[218:221], v161 offset:3072
	global_load_lds_dwordx4 v[158:159], off
	v_lshl_add_u64 v[158:159], v[182:183], 0, s[10:11]
	s_add_i32 m0, s27, 0x2000
	s_nop 0
	global_load_lds_dwordx4 v[158:159], off
	s_barrier
	s_waitcnt lgkmcnt(0)
	s_waitcnt lgkmcnt(0)
	v_mfma_f32_16x16x32_bf16 v[120:123], v[206:209], v[170:173], v[120:123]
	v_mfma_f32_16x16x32_bf16 v[112:115], v[214:217], v[170:173], v[112:115]
	v_mfma_f32_16x16x32_bf16 v[104:107], v[206:209], v[178:181], v[104:107]
	v_mfma_f32_16x16x32_bf16 v[96:99], v[214:217], v[178:181], v[96:99]
	v_mfma_f32_16x16x32_bf16 v[88:91], v[206:209], v[190:193], v[88:91]
	v_mfma_f32_16x16x32_bf16 v[80:83], v[214:217], v[190:193], v[80:83]
	v_mfma_f32_16x16x32_bf16 v[72:75], v[206:209], v[198:201], v[72:75]
	v_mfma_f32_16x16x32_bf16 v[64:67], v[214:217], v[198:201], v[64:67]
	v_mfma_f32_16x16x32_bf16 v[120:123], v[210:213], v[174:177], v[120:123]
	v_mfma_f32_16x16x32_bf16 v[112:115], v[218:221], v[174:177], v[112:115]
	v_mfma_f32_16x16x32_bf16 v[104:107], v[210:213], v[186:189], v[104:107]
	v_mfma_f32_16x16x32_bf16 v[96:99], v[218:221], v[186:189], v[96:99]
	v_mfma_f32_16x16x32_bf16 v[88:91], v[210:213], v[194:197], v[88:91]
	v_mfma_f32_16x16x32_bf16 v[80:83], v[218:221], v[194:197], v[80:83]
	v_mfma_f32_16x16x32_bf16 v[72:75], v[210:213], v[202:205], v[72:75]
	v_mfma_f32_16x16x32_bf16 v[64:67], v[218:221], v[202:205], v[64:67]
	s_mov_b32 m0, s42
	v_lshl_add_u64 v[158:159], v[222:223], 0, s[10:11]
	s_barrier
	ds_read_b128 v[170:173], v148 offset:49152
	ds_read_b128 v[174:177], v148 offset:50176
	ds_read_b128 v[178:181], v148 offset:51200
	ds_read_b128 v[186:189], v148 offset:52224
	ds_read_b128 v[190:193], v148 offset:53248
	ds_read_b128 v[194:197], v148 offset:54272
	ds_read_b128 v[198:201], v148 offset:55296
	ds_read_b128 v[202:205], v148 offset:56320
	global_load_lds_dwordx4 v[158:159], off
	v_lshl_add_u64 v[158:159], v[224:225], 0, s[10:11]
	s_mov_b32 m0, s43
	s_nop 0
	global_load_lds_dwordx4 v[158:159], off
	s_barrier
	s_waitcnt lgkmcnt(0)
	s_waitcnt lgkmcnt(0)
	v_mfma_f32_16x16x32_bf16 v[60:63], v[150:153], v[170:173], v[60:63]
	v_mfma_f32_16x16x32_bf16 v[52:55], v[162:165], v[170:173], v[52:55]
	v_mfma_f32_16x16x32_bf16 v[44:47], v[150:153], v[178:181], v[44:47]
	v_mfma_f32_16x16x32_bf16 v[36:39], v[162:165], v[178:181], v[36:39]
	v_mfma_f32_16x16x32_bf16 v[28:31], v[150:153], v[190:193], v[28:31]
	v_mfma_f32_16x16x32_bf16 v[20:23], v[162:165], v[190:193], v[20:23]
	v_mfma_f32_16x16x32_bf16 v[12:15], v[150:153], v[198:201], v[12:15]
	v_mfma_f32_16x16x32_bf16 v[4:7], v[162:165], v[198:201], v[4:7]
	v_mfma_f32_16x16x32_bf16 v[60:63], v[154:157], v[174:177], v[60:63]
	v_mfma_f32_16x16x32_bf16 v[52:55], v[166:169], v[174:177], v[52:55]
	v_mfma_f32_16x16x32_bf16 v[44:47], v[154:157], v[186:189], v[44:47]
	v_mfma_f32_16x16x32_bf16 v[36:39], v[166:169], v[186:189], v[36:39]
	v_mfma_f32_16x16x32_bf16 v[28:31], v[154:157], v[194:197], v[28:31]
	v_mfma_f32_16x16x32_bf16 v[20:23], v[166:169], v[194:197], v[20:23]
	v_mfma_f32_16x16x32_bf16 v[12:15], v[154:157], v[202:205], v[12:15]
	v_mfma_f32_16x16x32_bf16 v[4:7], v[166:169], v[202:205], v[4:7]
	s_barrier
	s_add_u32 s24, s24, 0x80080
	s_addc_u32 s25, s25, 0
	s_add_i32 s26, s26, s34
	v_lshl_add_u64 v[150:151], s[24:25], 0, v[130:131]
	s_mov_b32 m0, s26
	s_nop 0
	global_load_lds_dwordx4 v[150:151], off
	v_lshl_add_u64 v[150:151], s[24:25], 0, v[134:135]
	s_add_i32 m0, s26, 0x2000
	s_nop 0
	global_load_lds_dwordx4 v[150:151], off
	s_waitcnt vmcnt(6)
	s_barrier
	v_mfma_f32_16x16x32_bf16 v[56:59], v[206:209], v[170:173], v[56:59]
	v_mfma_f32_16x16x32_bf16 v[48:51], v[214:217], v[170:173], v[48:51]
	v_mfma_f32_16x16x32_bf16 v[40:43], v[206:209], v[178:181], v[40:43]
	v_mfma_f32_16x16x32_bf16 v[32:35], v[214:217], v[178:181], v[32:35]
	v_mfma_f32_16x16x32_bf16 v[24:27], v[206:209], v[190:193], v[24:27]
	v_mfma_f32_16x16x32_bf16 v[16:19], v[214:217], v[190:193], v[16:19]
	v_mfma_f32_16x16x32_bf16 v[8:11], v[206:209], v[198:201], v[8:11]
	v_mfma_f32_16x16x32_bf16 v[0:3], v[214:217], v[198:201], v[0:3]
	v_mfma_f32_16x16x32_bf16 v[56:59], v[210:213], v[174:177], v[56:59]
	v_mfma_f32_16x16x32_bf16 v[48:51], v[218:221], v[174:177], v[48:51]
	v_mfma_f32_16x16x32_bf16 v[40:43], v[210:213], v[186:189], v[40:43]
	v_mfma_f32_16x16x32_bf16 v[32:35], v[218:221], v[186:189], v[32:35]
	v_mfma_f32_16x16x32_bf16 v[24:27], v[210:213], v[194:197], v[24:27]
	v_mfma_f32_16x16x32_bf16 v[16:19], v[218:221], v[194:197], v[16:19]
	v_mfma_f32_16x16x32_bf16 v[8:11], v[210:213], v[202:205], v[8:11]
	v_mfma_f32_16x16x32_bf16 v[0:3], v[218:221], v[202:205], v[0:3]
	s_add_i32 s52, s52, 2
	s_add_u32 s22, s22, 0x100
	s_addc_u32 s23, s23, 0
	s_add_u32 s50, s50, 0x100
	s_addc_u32 s51, s51, 0
	s_cmp_gt_u32 s52, 29
	s_barrier
; __device__ __forceinline__ u32x4 pack8(const float* f) { u32x4 w; w.x = pk2(f[0], f[1]); w.y = pk2(f[2], f[3]); w.z = pk2(f[4], f[5]); w.w = pk2(f[6], f[7]); return w; }
;     __device__ __forceinline__ void operator()(const Acc& acc, const Unit& u, int wr, int wc, int fr, int fq) const { if (u.piece == 0) e1(acc, u, wr, wc, fr, fq); else e2(acc, u, wr, wc, fr, fq); }
;     __device__ __forceinline__ void operator()(const Acc& acc, const Unit& u, int wr, int wc, int fr, int fq) const {
;         const int row0 = u.pm * BM + wr * 64 + fr, col0 = u.pn * HALF + wc * 32 + 8 * fq;
; #pragma unroll
;         for (int ai = 0; ai < 2; ++ai)
; #pragma unroll
;             for (int m = 0; m < 4; ++m) { float v[8];
; #pragma unroll
;                 for (int n = 0; n < 2; ++n) {
;                     const f32x4 gt = acc[ai][0][m][n], arg = gt * (-1.4426950408889634f), gu = gt * acc[ai][1][m][n];
;                     f32x4 t;
; #pragma unroll
;                     for (int j = 0; j < 4; ++j) t[j] = __builtin_amdgcn_exp2f(arg[j]);
;                     t = t + 1.0f;
; #pragma unroll
;                     for (int j = 0; j < 4; ++j) t[j] = __builtin_amdgcn_rcpf(t[j]);
;                     const f32x4 r = gu * t;
; #pragma unroll
;                     for (int j = 0; j < 4; ++j) v[4 * n + j] = r[j]; }
;                 *(u32x4*)(O + (size_t)(row0 + ai * HALF + m * 16) * DFF + col0) = pack8(v); }
	s_cbranch_scc0 .LBB0_1843
	s_setprio 0
	v_mul_f32_e32 v153, 0xbfb8aa3b, v126
	v_exp_f32_e32 v154, v153
	v_mul_f32_e32 v153, 0xbfb8aa3b, v127
	v_mul_f32_e32 v151, 0xbfb8aa3b, v124
	v_exp_f32_e32 v155, v153
	v_exp_f32_e32 v152, v151
	v_mul_f32_e32 v151, 0xbfb8aa3b, v125
	v_pk_mul_f32 v[120:121], v[120:121], v[124:125]
	v_mul_f32_e32 v124, 0xbfb8aa3b, v116
	v_mul_f32_e32 v125, 0xbfb8aa3b, v117
	v_pk_mul_f32 v[122:123], v[122:123], v[126:127]
	v_exp_f32_e32 v124, v124
	v_mul_f32_e32 v126, 0xbfb8aa3b, v118
	v_mul_f32_e32 v127, 0xbfb8aa3b, v119
	v_exp_f32_e32 v125, v125
	v_exp_f32_e32 v153, v151
	v_exp_f32_e32 v126, v126
	v_exp_f32_e32 v127, v127
	v_pk_add_f32 v[154:155], v[154:155], 1.0 op_sel_hi:[1,0]
	v_pk_add_f32 v[124:125], v[124:125], 1.0 op_sel_hi:[1,0]
	v_rcp_f32_e32 v154, v154
	v_rcp_f32_e32 v155, v155
	v_pk_add_f32 v[152:153], v[152:153], 1.0 op_sel_hi:[1,0]
	v_pk_add_f32 v[126:127], v[126:127], 1.0 op_sel_hi:[1,0]
	v_rcp_f32_e32 v124, v124
	v_rcp_f32_e32 v125, v125
	v_rcp_f32_e32 v152, v152
	v_rcp_f32_e32 v153, v153
	v_rcp_f32_e32 v126, v126
	v_rcp_f32_e32 v127, v127
	v_pk_mul_f32 v[122:123], v[122:123], v[154:155]
	v_pk_mul_f32 v[112:113], v[112:113], v[116:117]
	v_cvt_pk_bf16_f32 v117, v122, v123
	v_mul_f32_e32 v122, 0xbfb8aa3b, v108
	v_mul_f32_e32 v123, 0xbfb8aa3b, v109
	v_lshl_or_b32 v156, s47, 7, v146
	v_pk_mul_f32 v[114:115], v[114:115], v[118:119]
	v_pk_mul_f32 v[112:113], v[112:113], v[124:125]
	v_exp_f32_e32 v122, v122
	v_mul_f32_e32 v124, 0xbfb8aa3b, v110
	v_mul_f32_e32 v125, 0xbfb8aa3b, v111
	v_exp_f32_e32 v123, v123
	v_pk_mul_f32 v[106:107], v[106:107], v[110:111]
	v_pk_mul_f32 v[104:105], v[104:105], v[108:109]
	v_mul_f32_e32 v108, 0xbfb8aa3b, v100
	v_mul_f32_e32 v109, 0xbfb8aa3b, v101
	v_mul_f32_e32 v110, 0xbfb8aa3b, v102
	v_mul_f32_e32 v111, 0xbfb8aa3b, v103
	v_lshl_add_u32 v150, s20, 8, v144
	v_ashrrev_i32_e32 v157, 31, v156
	v_pk_mul_f32 v[120:121], v[120:121], v[152:153]
	v_pk_mul_f32 v[114:115], v[114:115], v[126:127]
	v_cvt_pk_bf16_f32 v118, v112, v113
	v_mov_b64_e32 v[112:113], s[8:9]
	v_exp_f32_e32 v108, v108
	v_exp_f32_e32 v110, v110
	v_exp_f32_e32 v111, v111
	v_exp_f32_e32 v109, v109
	v_cvt_pk_bf16_f32 v116, v120, v121
	v_cvt_pk_bf16_f32 v119, v114, v115
	v_mad_i64_i32 v[120:121], s[22:23], v150, s46, v[112:113]
	v_lshlrev_b64 v[114:115], 1, v[156:157]
	v_lshl_add_u64 v[120:121], v[120:121], 0, v[114:115]
	global_store_dwordx4 v[120:121], v[116:119], off
	v_exp_f32_e32 v124, v124
	v_exp_f32_e32 v125, v125
	v_pk_add_f32 v[118:119], v[122:123], 1.0 op_sel_hi:[1,0]
	v_pk_add_f32 v[110:111], v[110:111], 1.0 op_sel_hi:[1,0]
	v_rcp_f32_e32 v118, v118
	v_rcp_f32_e32 v119, v119
	v_pk_add_f32 v[108:109], v[108:109], 1.0 op_sel_hi:[1,0]
	v_rcp_f32_e32 v110, v110
	v_rcp_f32_e32 v108, v108
	v_rcp_f32_e32 v109, v109
	v_rcp_f32_e32 v111, v111
	v_pk_add_f32 v[116:117], v[124:125], 1.0 op_sel_hi:[1,0]
	v_pk_mul_f32 v[104:105], v[104:105], v[118:119]
	v_pk_mul_f32 v[98:99], v[98:99], v[102:103]
	v_pk_mul_f32 v[96:97], v[96:97], v[100:101]
	v_rcp_f32_e32 v116, v116
	v_rcp_f32_e32 v117, v117
	v_pk_mul_f32 v[100:101], v[96:97], v[108:109]
	v_pk_mul_f32 v[102:103], v[98:99], v[110:111]
	v_cvt_pk_bf16_f32 v96, v104, v105
	v_mul_f32_e32 v104, 0xbfb8aa3b, v94
	v_mul_f32_e32 v105, 0xbfb8aa3b, v95
	v_pk_mul_f32 v[90:91], v[90:91], v[94:95]
	v_mul_f32_e32 v94, 0xbfb8aa3b, v86
	v_mul_f32_e32 v95, 0xbfb8aa3b, v87
	v_cvt_pk_bf16_f32 v99, v102, v103
	v_mul_f32_e32 v102, 0xbfb8aa3b, v92
	v_mul_f32_e32 v103, 0xbfb8aa3b, v93
	v_exp_f32_e32 v94, v94
	v_exp_f32_e32 v95, v95
	v_exp_f32_e32 v102, v102
	v_exp_f32_e32 v103, v103
	v_pk_mul_f32 v[88:89], v[88:89], v[92:93]
	v_mul_f32_e32 v92, 0xbfb8aa3b, v84
	v_mul_f32_e32 v93, 0xbfb8aa3b, v85
	v_cvt_pk_bf16_f32 v98, v100, v101
	v_or_b32_e32 v100, 16, v150
	v_exp_f32_e32 v92, v92
	v_exp_f32_e32 v93, v93
	v_pk_mul_f32 v[106:107], v[106:107], v[116:117]
	v_mad_i64_i32 v[100:101], s[22:23], v100, s46, v[112:113]
	v_cvt_pk_bf16_f32 v97, v106, v107
	v_exp_f32_e32 v104, v104
	v_exp_f32_e32 v105, v105
	v_lshl_add_u64 v[100:101], v[100:101], 0, v[114:115]
	v_pk_add_f32 v[94:95], v[94:95], 1.0 op_sel_hi:[1,0]
	global_store_dwordx4 v[100:101], v[96:99], off
	v_rcp_f32_e32 v94, v94
	v_rcp_f32_e32 v95, v95
	v_pk_add_f32 v[98:99], v[102:103], 1.0 op_sel_hi:[1,0]
	v_pk_add_f32 v[92:93], v[92:93], 1.0 op_sel_hi:[1,0]
	v_rcp_f32_e32 v98, v98
	v_rcp_f32_e32 v99, v99
	v_rcp_f32_e32 v92, v92
	v_rcp_f32_e32 v93, v93
	v_pk_add_f32 v[96:97], v[104:105], 1.0 op_sel_hi:[1,0]
	v_pk_mul_f32 v[82:83], v[82:83], v[86:87]
	v_rcp_f32_e32 v96, v96
	v_rcp_f32_e32 v97, v97
	v_pk_mul_f32 v[86:87], v[82:83], v[94:95]
	v_pk_mul_f32 v[88:89], v[88:89], v[98:99]
	v_pk_mul_f32 v[80:81], v[80:81], v[84:85]
	v_cvt_pk_bf16_f32 v83, v86, v87
	v_mul_f32_e32 v86, 0xbfb8aa3b, v76
	v_mul_f32_e32 v87, 0xbfb8aa3b, v77
	v_pk_mul_f32 v[84:85], v[80:81], v[92:93]
	v_cvt_pk_bf16_f32 v80, v88, v89
	v_exp_f32_e32 v86, v86
	v_mul_f32_e32 v88, 0xbfb8aa3b, v78
	v_mul_f32_e32 v89, 0xbfb8aa3b, v79
	v_exp_f32_e32 v87, v87
	v_pk_mul_f32 v[74:75], v[74:75], v[78:79]
	v_pk_mul_f32 v[72:73], v[72:73], v[76:77]
	v_mul_f32_e32 v76, 0xbfb8aa3b, v68
	v_mul_f32_e32 v77, 0xbfb8aa3b, v69
	v_mul_f32_e32 v78, 0xbfb8aa3b, v70
	v_mul_f32_e32 v79, 0xbfb8aa3b, v71
	v_cvt_pk_bf16_f32 v82, v84, v85
	v_or_b32_e32 v84, 32, v150
	v_exp_f32_e32 v76, v76
	v_exp_f32_e32 v78, v78
	v_exp_f32_e32 v79, v79
	v_exp_f32_e32 v77, v77
	v_pk_mul_f32 v[90:91], v[90:91], v[96:97]
	v_mad_i64_i32 v[84:85], s[22:23], v84, s46, v[112:113]
	v_cvt_pk_bf16_f32 v81, v90, v91
	v_lshl_add_u64 v[84:85], v[84:85], 0, v[114:115]
	global_store_dwordx4 v[84:85], v[80:83], off
	v_exp_f32_e32 v88, v88
; __device__ __forceinline__ u32x4 pack8(const float* f) { u32x4 w; w.x = pk2(f[0], f[1]); w.y = pk2(f[2], f[3]); w.z = pk2(f[4], f[5]); w.w = pk2(f[6], f[7]); return w; }
;     __device__ __forceinline__ void operator()(const Acc& acc, const Unit& u, int wr, int wc, int fr, int fq) const {
;     ...
;             for (int m = 0; m < 4; ++m) { float v[8];
; #pragma unroll
;                 for (int n = 0; n < 2; ++n) {
;                     const f32x4 gt = acc[ai][0][m][n], arg = gt * (-1.4426950408889634f), gu = gt * acc[ai][1][m][n];
;                     f32x4 t;
; #pragma unroll
;                     for (int j = 0; j < 4; ++j) t[j] = __builtin_amdgcn_exp2f(arg[j]);
;                     t = t + 1.0f;
; #pragma unroll
;                     for (int j = 0; j < 4; ++j) t[j] = __builtin_amdgcn_rcpf(t[j]);
;                     const f32x4 r = gu * t;
; #pragma unroll
;                     for (int j = 0; j < 4; ++j) v[4 * n + j] = r[j]; }
;                 *(u32x4*)(O + (size_t)(row0 + ai * HALF + m * 16) * DFF + col0) = pack8(v); }
	v_exp_f32_e32 v89, v89
	v_pk_add_f32 v[82:83], v[86:87], 1.0 op_sel_hi:[1,0]
	v_pk_add_f32 v[78:79], v[78:79], 1.0 op_sel_hi:[1,0]
	v_rcp_f32_e32 v82, v82
	v_rcp_f32_e32 v83, v83
	v_pk_add_f32 v[76:77], v[76:77], 1.0 op_sel_hi:[1,0]
	v_rcp_f32_e32 v78, v78
	v_rcp_f32_e32 v76, v76
	v_rcp_f32_e32 v77, v77
	v_rcp_f32_e32 v79, v79
	v_pk_add_f32 v[80:81], v[88:89], 1.0 op_sel_hi:[1,0]
	v_pk_mul_f32 v[72:73], v[72:73], v[82:83]
	v_pk_mul_f32 v[66:67], v[66:67], v[70:71]
	v_pk_mul_f32 v[64:65], v[64:65], v[68:69]
	v_rcp_f32_e32 v80, v80
	v_rcp_f32_e32 v81, v81
	v_pk_mul_f32 v[68:69], v[64:65], v[76:77]
	v_pk_mul_f32 v[70:71], v[66:67], v[78:79]
	v_cvt_pk_bf16_f32 v64, v72, v73
	v_mul_f32_e32 v72, 0xbfb8aa3b, v62
	v_mul_f32_e32 v73, 0xbfb8aa3b, v63
	v_pk_mul_f32 v[58:59], v[58:59], v[62:63]
	v_mul_f32_e32 v62, 0xbfb8aa3b, v54
	v_mul_f32_e32 v63, 0xbfb8aa3b, v55
	v_cvt_pk_bf16_f32 v67, v70, v71
	v_mul_f32_e32 v70, 0xbfb8aa3b, v60
	v_mul_f32_e32 v71, 0xbfb8aa3b, v61
	v_exp_f32_e32 v62, v62
	v_exp_f32_e32 v63, v63
	v_exp_f32_e32 v70, v70
	v_exp_f32_e32 v71, v71
	v_pk_mul_f32 v[56:57], v[56:57], v[60:61]
	v_mul_f32_e32 v60, 0xbfb8aa3b, v52
	v_mul_f32_e32 v61, 0xbfb8aa3b, v53
	v_cvt_pk_bf16_f32 v66, v68, v69
	v_or_b32_e32 v68, 48, v150
	v_exp_f32_e32 v60, v60
	v_exp_f32_e32 v61, v61
	v_pk_mul_f32 v[74:75], v[74:75], v[80:81]
	v_mad_i64_i32 v[68:69], s[22:23], v68, s46, v[112:113]
	v_cvt_pk_bf16_f32 v65, v74, v75
	v_lshl_add_u64 v[68:69], v[68:69], 0, v[114:115]
	v_exp_f32_e32 v72, v72
	v_exp_f32_e32 v73, v73
	v_pk_add_f32 v[62:63], v[62:63], 1.0 op_sel_hi:[1,0]
	global_store_dwordx4 v[68:69], v[64:67], off
	v_rcp_f32_e32 v62, v62
	v_rcp_f32_e32 v63, v63
	v_pk_add_f32 v[66:67], v[70:71], 1.0 op_sel_hi:[1,0]
	v_pk_add_f32 v[60:61], v[60:61], 1.0 op_sel_hi:[1,0]
	v_rcp_f32_e32 v66, v66
	v_rcp_f32_e32 v67, v67
	v_rcp_f32_e32 v60, v60
	v_rcp_f32_e32 v61, v61
	v_pk_add_f32 v[64:65], v[72:73], 1.0 op_sel_hi:[1,0]
	v_pk_mul_f32 v[50:51], v[50:51], v[54:55]
	v_rcp_f32_e32 v64, v64
	v_rcp_f32_e32 v65, v65
	v_pk_mul_f32 v[54:55], v[50:51], v[62:63]
	v_pk_mul_f32 v[56:57], v[56:57], v[66:67]
	v_pk_mul_f32 v[48:49], v[48:49], v[52:53]
	v_cvt_pk_bf16_f32 v51, v54, v55
	v_mul_f32_e32 v54, 0xbfb8aa3b, v44
	v_mul_f32_e32 v55, 0xbfb8aa3b, v45
	v_pk_mul_f32 v[52:53], v[48:49], v[60:61]
	v_cvt_pk_bf16_f32 v48, v56, v57
	v_exp_f32_e32 v54, v54
	v_mul_f32_e32 v56, 0xbfb8aa3b, v46
	v_mul_f32_e32 v57, 0xbfb8aa3b, v47
	v_exp_f32_e32 v55, v55
	v_pk_mul_f32 v[42:43], v[42:43], v[46:47]
	v_pk_mul_f32 v[40:41], v[40:41], v[44:45]
	v_mul_f32_e32 v44, 0xbfb8aa3b, v36
	v_mul_f32_e32 v45, 0xbfb8aa3b, v37
	v_mul_f32_e32 v46, 0xbfb8aa3b, v38
	v_mul_f32_e32 v47, 0xbfb8aa3b, v39
	v_add_u32_e32 v68, 0x80, v150
	v_exp_f32_e32 v44, v44
	v_exp_f32_e32 v46, v46
	v_exp_f32_e32 v47, v47
	v_exp_f32_e32 v45, v45
	v_pk_mul_f32 v[58:59], v[58:59], v[64:65]
	v_cvt_pk_bf16_f32 v50, v52, v53
	v_mad_i64_i32 v[52:53], s[22:23], v68, s46, v[112:113]
	v_cvt_pk_bf16_f32 v49, v58, v59
	v_lshl_add_u64 v[52:53], v[52:53], 0, v[114:115]
	global_store_dwordx4 v[52:53], v[48:51], off
	v_exp_f32_e32 v56, v56
	v_exp_f32_e32 v57, v57
	v_pk_add_f32 v[50:51], v[54:55], 1.0 op_sel_hi:[1,0]
	v_pk_add_f32 v[46:47], v[46:47], 1.0 op_sel_hi:[1,0]
	v_rcp_f32_e32 v50, v50
	v_rcp_f32_e32 v51, v51
	v_pk_add_f32 v[44:45], v[44:45], 1.0 op_sel_hi:[1,0]
	v_rcp_f32_e32 v46, v46
	v_rcp_f32_e32 v44, v44
	v_rcp_f32_e32 v45, v45
	v_rcp_f32_e32 v47, v47
	v_pk_add_f32 v[48:49], v[56:57], 1.0 op_sel_hi:[1,0]
	v_pk_mul_f32 v[40:41], v[40:41], v[50:51]
	v_pk_mul_f32 v[34:35], v[34:35], v[38:39]
	v_pk_mul_f32 v[32:33], v[32:33], v[36:37]
	v_rcp_f32_e32 v48, v48
	v_rcp_f32_e32 v49, v49
	v_pk_mul_f32 v[36:37], v[32:33], v[44:45]
; __device__ __forceinline__ u32x4 pack8(const float* f) { u32x4 w; w.x = pk2(f[0], f[1]); w.y = pk2(f[2], f[3]); w.z = pk2(f[4], f[5]); w.w = pk2(f[6], f[7]); return w; }
; #define PG8_WAIT_V(n) asm volatile("s_waitcnt vmcnt(" #n ")" ::: "memory")
; #define PG8_BAR __builtin_amdgcn_s_barrier()
; template <class Epi, class Sched>
; __device__ __forceinline__ void gemm_phase(LAS unsigned char* lds, const Gemm g, const Sched& S, const Epi& E) {
;     ...
;         cur = nxt; cA = nA; cB = nB; ++ui;
;     }
;     PG8_WAIT_V(0);
;     if (wr == 0) PG8_BAR;
;     __device__ __forceinline__ void operator()(const Acc& acc, const Unit& u, int wr, int wc, int fr, int fq) const {
;     ...
;                 for (int n = 0; n < 2; ++n) {
;                     const f32x4 gt = acc[ai][0][m][n], arg = gt * (-1.4426950408889634f), gu = gt * acc[ai][1][m][n];
;                     f32x4 t;
; #pragma unroll
;                     for (int j = 0; j < 4; ++j) t[j] = __builtin_amdgcn_exp2f(arg[j]);
;                     t = t + 1.0f;
; #pragma unroll
;                     for (int j = 0; j < 4; ++j) t[j] = __builtin_amdgcn_rcpf(t[j]);
;                     const f32x4 r = gu * t;
; #pragma unroll
;                     for (int j = 0; j < 4; ++j) v[4 * n + j] = r[j]; }
;                 *(u32x4*)(O + (size_t)(row0 + ai * HALF + m * 16) * DFF + col0) = pack8(v); }
	v_pk_mul_f32 v[38:39], v[34:35], v[46:47]
	v_cvt_pk_bf16_f32 v32, v40, v41
	v_mul_f32_e32 v40, 0xbfb8aa3b, v30
	v_mul_f32_e32 v41, 0xbfb8aa3b, v31
	v_pk_mul_f32 v[26:27], v[26:27], v[30:31]
	v_mul_f32_e32 v30, 0xbfb8aa3b, v22
	v_mul_f32_e32 v31, 0xbfb8aa3b, v23
	v_cvt_pk_bf16_f32 v35, v38, v39
	v_mul_f32_e32 v38, 0xbfb8aa3b, v28
	v_mul_f32_e32 v39, 0xbfb8aa3b, v29
	v_exp_f32_e32 v30, v30
	v_exp_f32_e32 v31, v31
	v_exp_f32_e32 v38, v38
	v_exp_f32_e32 v39, v39
	v_pk_mul_f32 v[24:25], v[24:25], v[28:29]
	v_mul_f32_e32 v28, 0xbfb8aa3b, v20
	v_mul_f32_e32 v29, 0xbfb8aa3b, v21
	v_cvt_pk_bf16_f32 v34, v36, v37
	v_add_u32_e32 v36, 0x90, v150
	v_exp_f32_e32 v28, v28
	v_exp_f32_e32 v29, v29
	v_pk_mul_f32 v[42:43], v[42:43], v[48:49]
	v_mad_i64_i32 v[36:37], s[22:23], v36, s46, v[112:113]
	v_cvt_pk_bf16_f32 v33, v42, v43
	v_lshl_add_u64 v[36:37], v[36:37], 0, v[114:115]
	v_pk_add_f32 v[30:31], v[30:31], 1.0 op_sel_hi:[1,0]
	global_store_dwordx4 v[36:37], v[32:35], off
	v_rcp_f32_e32 v30, v30
	v_rcp_f32_e32 v31, v31
	v_pk_add_f32 v[34:35], v[38:39], 1.0 op_sel_hi:[1,0]
	v_exp_f32_e32 v40, v40
	v_exp_f32_e32 v41, v41
	v_rcp_f32_e32 v34, v34
	v_rcp_f32_e32 v35, v35
	v_pk_add_f32 v[28:29], v[28:29], 1.0 op_sel_hi:[1,0]
	v_pk_mul_f32 v[18:19], v[18:19], v[22:23]
	v_rcp_f32_e32 v28, v28
	v_rcp_f32_e32 v29, v29
	v_pk_mul_f32 v[22:23], v[18:19], v[30:31]
	v_pk_add_f32 v[32:33], v[40:41], 1.0 op_sel_hi:[1,0]
	v_pk_mul_f32 v[24:25], v[24:25], v[34:35]
	v_pk_mul_f32 v[16:17], v[16:17], v[20:21]
	v_cvt_pk_bf16_f32 v19, v22, v23
	v_mul_f32_e32 v22, 0xbfb8aa3b, v12
	v_mul_f32_e32 v23, 0xbfb8aa3b, v13
	v_pk_mul_f32 v[8:9], v[8:9], v[12:13]
	v_mul_f32_e32 v12, 0xbfb8aa3b, v4
	v_mul_f32_e32 v13, 0xbfb8aa3b, v5
	v_rcp_f32_e32 v32, v32
	v_rcp_f32_e32 v33, v33
	v_pk_mul_f32 v[20:21], v[16:17], v[28:29]
	v_cvt_pk_bf16_f32 v16, v24, v25
	v_mul_f32_e32 v24, 0xbfb8aa3b, v14
	v_mul_f32_e32 v25, 0xbfb8aa3b, v15
	v_pk_mul_f32 v[10:11], v[10:11], v[14:15]
	v_exp_f32_e32 v12, v12
	v_mul_f32_e32 v14, 0xbfb8aa3b, v6
	v_mul_f32_e32 v15, 0xbfb8aa3b, v7
	v_exp_f32_e32 v13, v13
	v_exp_f32_e32 v14, v14
	v_exp_f32_e32 v15, v15
	v_exp_f32_e32 v22, v22
	v_exp_f32_e32 v24, v24
	v_exp_f32_e32 v25, v25
	v_exp_f32_e32 v23, v23
	v_cvt_pk_bf16_f32 v18, v20, v21
	v_add_u32_e32 v20, 0xa0, v150
	v_pk_mul_f32 v[26:27], v[26:27], v[32:33]
	v_mad_i64_i32 v[20:21], s[22:23], v20, s46, v[112:113]
	v_pk_add_f32 v[12:13], v[12:13], 1.0 op_sel_hi:[1,0]
	v_cvt_pk_bf16_f32 v17, v26, v27
	v_lshl_add_u64 v[20:21], v[20:21], 0, v[114:115]
	v_pk_add_f32 v[14:15], v[14:15], 1.0 op_sel_hi:[1,0]
	v_rcp_f32_e32 v12, v12
	v_rcp_f32_e32 v13, v13
	global_store_dwordx4 v[20:21], v[16:19], off
	v_rcp_f32_e32 v14, v14
	v_rcp_f32_e32 v15, v15
	v_pk_add_f32 v[16:17], v[24:25], 1.0 op_sel_hi:[1,0]
	v_pk_add_f32 v[18:19], v[22:23], 1.0 op_sel_hi:[1,0]
	v_rcp_f32_e32 v16, v16
	v_rcp_f32_e32 v18, v18
	v_rcp_f32_e32 v19, v19
	v_rcp_f32_e32 v17, v17
	v_pk_mul_f32 v[0:1], v[0:1], v[4:5]
	v_pk_mul_f32 v[2:3], v[2:3], v[6:7]
	v_pk_mul_f32 v[4:5], v[0:1], v[12:13]
	v_pk_mul_f32 v[6:7], v[2:3], v[14:15]
	v_cvt_pk_bf16_f32 v2, v4, v5
	v_add_u32_e32 v4, 0xb0, v150
	v_pk_mul_f32 v[8:9], v[8:9], v[18:19]
	v_pk_mul_f32 v[10:11], v[10:11], v[16:17]
	v_mad_i64_i32 v[4:5], s[22:23], v4, s46, v[112:113]
	v_cvt_pk_bf16_f32 v0, v8, v9
	v_cvt_pk_bf16_f32 v1, v10, v11
	v_cvt_pk_bf16_f32 v3, v6, v7
	v_lshl_add_u64 v[4:5], v[4:5], 0, v[114:115]
	s_and_b64 vcc, exec, s[6:7]
	s_mov_b32 s47, s12
	s_mov_b32 s20, s14
	s_mov_b64 s[24:25], s[18:19]
	s_mov_b64 s[22:23], s[16:17]
	global_store_dwordx4 v[4:5], v[0:3], off
	s_cbranch_vccz .LBB0_1840
	s_waitcnt vmcnt(0)
	s_cmpk_gt_u32 s3, 0xff
	s_cbranch_scc1 .LBB0_1847
	s_barrier
